# residual loads of second half hoisted above first-half stores in w_o, w_co, FFN2-down epilogues (as in FFN1-down)
# speedup vs baseline: 1.0058x; 1.0022x over previous
.LBB0_374:
	s_nop 0
	s_nop 0
	s_mov_b32 s98, 0x15000
	s_mov_b32 s99, 0x0
	v_lshl_add_u64 v[244:245], v[166:167], 0, s[98:99]
	s_mov_b32 s98, 0x5000
	s_mov_b32 s99, 0x0
	v_lshl_add_u64 v[246:247], v[166:167], 0, s[98:99]
	global_load_dwordx4 v[122:125], v[246:247], off offset:-4096
	global_load_dwordx4 v[126:129], v[244:245], off offset:-4096
	s_waitcnt vmcnt(8)
	v_lshlrev_b32_e32 v158, 16, v154
	v_and_b32_e32 v159, 0xffff0000, v154
	v_lshlrev_b32_e32 v154, 16, v155
	v_and_b32_e32 v155, 0xffff0000, v155
	v_pk_fma_f32 v[188:189], v[96:97], 0.5, v[154:155] op_sel_hi:[1,0,1]
	v_lshlrev_b32_e32 v154, 16, v156
	v_and_b32_e32 v155, 0xffff0000, v156
	v_pk_fma_f32 v[206:207], v[90:91], 0.5, v[154:155] op_sel_hi:[1,0,1]
	v_lshlrev_b32_e32 v154, 16, v157
	v_and_b32_e32 v155, 0xffff0000, v157
	v_pk_fma_f32 v[158:159], v[94:95], 0.5, v[158:159] op_sel_hi:[1,0,1]
	v_pk_fma_f32 v[208:209], v[92:93], 0.5, v[154:155] op_sel_hi:[1,0,1]
	v_cndmask_b32_e64 v165, 0, 1, s[54:55]
	v_cvt_pk_bf16_f32 v154, v158, v159
	v_cvt_pk_bf16_f32 v155, v188, v189
	v_cvt_pk_bf16_f32 v156, v206, v207
	v_cvt_pk_bf16_f32 v157, v208, v209
	v_cmp_ne_u32_e64 s[12:13], 1, v165
	s_andn2_b64 vcc, exec, s[54:55]
	s_mov_b64 s[14:15], -1
	s_cbranch_vccnz .LBB0_376
	s_mov_b64 s[14:15], 0
	global_store_dwordx4 v[172:173], v[154:157], off offset:-4096

.LBB0_384:
	s_or_b64 exec, exec, s[62:63]
	s_waitcnt lgkmcnt(0)
	global_load_dwordx4 v[90:93], v[246:247], off offset:-2048
	global_load_dwordx4 v[94:97], v[244:245], off offset:-2048
	s_waitcnt vmcnt(9)
	v_lshlrev_b32_e32 v154, 16, v150
	v_and_b32_e32 v155, 0xffff0000, v150
	v_lshlrev_b32_e32 v150, 16, v151
	v_and_b32_e32 v151, 0xffff0000, v151
	v_pk_fma_f32 v[156:157], v[120:121], 0.5, v[150:151] op_sel_hi:[1,0,1]
	v_lshlrev_b32_e32 v150, 16, v152
	v_and_b32_e32 v151, 0xffff0000, v152
	v_pk_fma_f32 v[158:159], v[114:115], 0.5, v[150:151] op_sel_hi:[1,0,1]
	v_lshlrev_b32_e32 v150, 16, v153
	v_and_b32_e32 v151, 0xffff0000, v153
	v_pk_fma_f32 v[154:155], v[118:119], 0.5, v[154:155] op_sel_hi:[1,0,1]
	v_pk_fma_f32 v[160:161], v[116:117], 0.5, v[150:151] op_sel_hi:[1,0,1]
	v_cvt_pk_bf16_f32 v150, v154, v155
	v_cvt_pk_bf16_f32 v151, v156, v157
	v_cvt_pk_bf16_f32 v152, v158, v159
	v_cvt_pk_bf16_f32 v153, v160, v161
	s_nor_b64 s[54:55], s[64:65], s[50:51]
	s_and_saveexec_b64 s[62:63], s[54:55]
	s_xor_b64 s[54:55], exec, s[62:63]
	s_cbranch_execz .LBB0_386
	global_store_dwordx4 v[174:175], v[150:153], off offset:-2048

.LBB0_388:
	s_or_b64 exec, exec, s[54:55]
	s_nop 0
	global_load_dwordx4 v[114:117], v[246:247], off
	global_load_dwordx4 v[118:121], v[244:245], off
	s_waitcnt vmcnt(10)
	v_lshlrev_b32_e32 v152, 16, v146
	v_and_b32_e32 v153, 0xffff0000, v146
	v_lshlrev_b32_e32 v146, 16, v147
	v_and_b32_e32 v147, 0xffff0000, v147
	v_pk_fma_f32 v[182:183], v[88:89], 0.5, v[146:147] op_sel_hi:[1,0,1]
	v_lshlrev_b32_e32 v146, 16, v148
	v_and_b32_e32 v147, 0xffff0000, v148
	v_pk_fma_f32 v[184:185], v[82:83], 0.5, v[146:147] op_sel_hi:[1,0,1]
	v_lshlrev_b32_e32 v146, 16, v149
	v_and_b32_e32 v147, 0xffff0000, v149
	v_pk_fma_f32 v[152:153], v[86:87], 0.5, v[152:153] op_sel_hi:[1,0,1]
	v_pk_fma_f32 v[186:187], v[84:85], 0.5, v[146:147] op_sel_hi:[1,0,1]
	v_cvt_pk_bf16_f32 v146, v152, v153
	v_cvt_pk_bf16_f32 v147, v182, v183
	v_cvt_pk_bf16_f32 v148, v184, v185
	v_cvt_pk_bf16_f32 v149, v186, v187
	s_and_b64 vcc, exec, s[12:13]
	s_mov_b64 s[54:55], -1
	s_cbranch_vccnz .LBB0_390
	s_mov_b64 s[54:55], 0
	global_store_dwordx4 v[172:173], v[146:149], off offset:-2048

.LBB0_398:
	s_or_b64 exec, exec, s[54:55]
	s_waitcnt lgkmcnt(0)
	global_load_dwordx4 v[82:85], v[246:247], off offset:2048
	global_load_dwordx4 v[86:89], v[244:245], off offset:2048
	s_waitcnt vmcnt(11)
	v_lshlrev_b32_e32 v146, 16, v142
	v_and_b32_e32 v147, 0xffff0000, v142
	v_lshlrev_b32_e32 v142, 16, v143
	v_and_b32_e32 v143, 0xffff0000, v143
	v_pk_fma_f32 v[148:149], v[112:113], 0.5, v[142:143] op_sel_hi:[1,0,1]
	v_lshlrev_b32_e32 v142, 16, v144
	v_and_b32_e32 v143, 0xffff0000, v144
	v_pk_fma_f32 v[150:151], v[106:107], 0.5, v[142:143] op_sel_hi:[1,0,1]
	v_lshlrev_b32_e32 v142, 16, v145
	v_and_b32_e32 v143, 0xffff0000, v145
	v_pk_fma_f32 v[146:147], v[110:111], 0.5, v[146:147] op_sel_hi:[1,0,1]
	v_pk_fma_f32 v[152:153], v[108:109], 0.5, v[142:143] op_sel_hi:[1,0,1]
	v_cvt_pk_bf16_f32 v142, v146, v147
	v_cvt_pk_bf16_f32 v143, v148, v149
	v_cvt_pk_bf16_f32 v144, v150, v151
	v_cvt_pk_bf16_f32 v145, v152, v153
	s_nor_b64 s[54:55], s[62:63], s[50:51]
	s_and_saveexec_b64 s[62:63], s[54:55]
	s_xor_b64 s[54:55], exec, s[62:63]
	s_cbranch_execz .LBB0_400
	global_store_dwordx4 v[174:175], v[142:145], off

.LBB0_402:
	s_or_b64 exec, exec, s[54:55]
	s_waitcnt vmcnt(10)
	v_lshlrev_b32_e32 v144, 16, v138
	v_and_b32_e32 v145, 0xffff0000, v138
	v_lshlrev_b32_e32 v138, 16, v139
	v_and_b32_e32 v139, 0xffff0000, v139
	v_pk_fma_f32 v[154:155], v[80:81], 0.5, v[138:139] op_sel_hi:[1,0,1]
	v_lshlrev_b32_e32 v138, 16, v140
	v_and_b32_e32 v139, 0xffff0000, v140
	v_pk_fma_f32 v[156:157], v[74:75], 0.5, v[138:139] op_sel_hi:[1,0,1]
	v_lshlrev_b32_e32 v138, 16, v141
	v_and_b32_e32 v139, 0xffff0000, v141
	v_pk_fma_f32 v[144:145], v[78:79], 0.5, v[144:145] op_sel_hi:[1,0,1]
	v_pk_fma_f32 v[158:159], v[76:77], 0.5, v[138:139] op_sel_hi:[1,0,1]
	v_cvt_pk_bf16_f32 v138, v144, v145
	v_cvt_pk_bf16_f32 v139, v154, v155
	v_cvt_pk_bf16_f32 v140, v156, v157
	v_cvt_pk_bf16_f32 v141, v158, v159
	s_and_b64 vcc, exec, s[12:13]
	s_mov_b64 s[54:55], -1
	s_cbranch_vccnz .LBB0_404
	s_mov_b64 s[54:55], 0
	global_store_dwordx4 v[172:173], v[138:141], off

.LBB0_412:
	s_or_b64 exec, exec, s[54:55]
	s_waitcnt lgkmcnt(0)
	s_waitcnt vmcnt(9)
	v_lshlrev_b32_e32 v138, 16, v134
	v_and_b32_e32 v139, 0xffff0000, v134
	v_lshlrev_b32_e32 v134, 16, v135
	v_and_b32_e32 v135, 0xffff0000, v135
	v_pk_fma_f32 v[140:141], v[104:105], 0.5, v[134:135] op_sel_hi:[1,0,1]
	v_lshlrev_b32_e32 v134, 16, v136
	v_and_b32_e32 v135, 0xffff0000, v136
	v_pk_fma_f32 v[142:143], v[98:99], 0.5, v[134:135] op_sel_hi:[1,0,1]
	v_lshlrev_b32_e32 v134, 16, v137
	v_and_b32_e32 v135, 0xffff0000, v137
	v_pk_fma_f32 v[138:139], v[102:103], 0.5, v[138:139] op_sel_hi:[1,0,1]
	v_pk_fma_f32 v[144:145], v[100:101], 0.5, v[134:135] op_sel_hi:[1,0,1]
	v_cvt_pk_bf16_f32 v134, v138, v139
	v_cvt_pk_bf16_f32 v135, v140, v141
	v_cvt_pk_bf16_f32 v136, v142, v143
	v_cvt_pk_bf16_f32 v137, v144, v145
	s_nor_b64 s[54:55], s[62:63], s[50:51]
	s_and_saveexec_b64 s[62:63], s[54:55]
	s_xor_b64 s[54:55], exec, s[62:63]
	s_cbranch_execz .LBB0_414
	global_store_dwordx4 v[174:175], v[134:137], off offset:2048

.LBB0_416:
	s_or_b64 exec, exec, s[54:55]
	s_waitcnt vmcnt(8)
	v_lshlrev_b32_e32 v136, 16, v130
	v_and_b32_e32 v137, 0xffff0000, v130
	v_lshlrev_b32_e32 v130, 16, v131
	v_and_b32_e32 v131, 0xffff0000, v131
	v_pk_fma_f32 v[146:147], v[72:73], 0.5, v[130:131] op_sel_hi:[1,0,1]
	v_lshlrev_b32_e32 v130, 16, v132
	v_and_b32_e32 v131, 0xffff0000, v132
	v_pk_fma_f32 v[148:149], v[66:67], 0.5, v[130:131] op_sel_hi:[1,0,1]
	v_lshlrev_b32_e32 v130, 16, v133
	v_and_b32_e32 v131, 0xffff0000, v133
	v_pk_fma_f32 v[136:137], v[70:71], 0.5, v[136:137] op_sel_hi:[1,0,1]
	v_pk_fma_f32 v[150:151], v[68:69], 0.5, v[130:131] op_sel_hi:[1,0,1]
	v_cvt_pk_bf16_f32 v130, v136, v137
	v_cvt_pk_bf16_f32 v131, v146, v147
	v_cvt_pk_bf16_f32 v132, v148, v149
	v_cvt_pk_bf16_f32 v133, v150, v151
	s_and_b64 vcc, exec, s[12:13]
	s_mov_b64 s[54:55], -1
	s_cbranch_vccnz .LBB0_418
	s_mov_b64 s[54:55], 0
	global_store_dwordx4 v[172:173], v[130:133], off offset:2048

.LBB0_425:
	s_or_b64 exec, exec, s[54:55]
	v_add_u32_e32 v184, 0x80, v162
	s_waitcnt lgkmcnt(0)
	v_lshlrev_b32_e32 v131, 6, v184
	v_lshlrev_b32_e32 v132, 2, v184
	v_lshlrev_b32_e32 v130, 7, v184
	v_and_b32_e32 v131, 0x3c0, v131
	v_and_b32_e32 v132, 32, v132
	v_and_b32_e32 v130, 0x4000, v130
	v_bitop3_b32 v131, v131, v132, v223 bitop3:0x36
	v_or3_b32 v198, v130, v131, v226
	v_add_u32_e32 v176, 0x90, v162
	s_mov_b32 s98, 0x5000
	s_mov_b32 s99, 0x0
	v_lshl_add_u64 v[172:173], v[166:167], 0, s[98:99]
	s_waitcnt vmcnt(4)
	v_mov_b32_e32 v158, v122
	v_mov_b32_e32 v159, v123
	v_mov_b32_e32 v160, v124
	v_mov_b32_e32 v161, v125
	s_mov_b32 s98, 0x15000
	s_mov_b32 s99, 0x0
	v_lshl_add_u64 v[174:175], v[166:167], 0, s[98:99]
	v_mov_b32_e32 v154, v126
	v_mov_b32_e32 v155, v127
	v_mov_b32_e32 v156, v128
	v_mov_b32_e32 v157, v129
	v_add_u32_e32 v168, 0xa0, v162
	v_mov_b32_e32 v150, v90
	v_mov_b32_e32 v151, v91
	v_mov_b32_e32 v152, v92
	v_mov_b32_e32 v153, v93
	v_mov_b32_e32 v146, v94
	v_mov_b32_e32 v147, v95
	v_mov_b32_e32 v148, v96
	v_mov_b32_e32 v149, v97
	v_add_u32_e32 v162, 0xb0, v162
	v_mov_b32_e32 v142, v114
	v_mov_b32_e32 v143, v115
	v_mov_b32_e32 v144, v116
	v_mov_b32_e32 v145, v117
	v_mov_b32_e32 v138, v118
	v_mov_b32_e32 v139, v119
	v_mov_b32_e32 v140, v120
	v_mov_b32_e32 v141, v121
	v_mov_b32_e32 v134, v82
	v_mov_b32_e32 v135, v83
	v_mov_b32_e32 v136, v84
	v_mov_b32_e32 v137, v85
	s_nop 0
	v_mov_b32_e32 v130, v86
	v_mov_b32_e32 v131, v87
	v_mov_b32_e32 v132, v88
	v_mov_b32_e32 v133, v89
	s_and_b64 vcc, exec, s[12:13]
	s_mov_b64 s[54:55], -1
	v_lshlrev_b32_e32 v190, 16, v158
	v_and_b32_e32 v191, 0xffff0000, v158
	v_lshlrev_b32_e32 v158, 16, v159
	v_and_b32_e32 v159, 0xffff0000, v159
	v_pk_fma_f32 v[192:193], v[64:65], 0.5, v[158:159] op_sel_hi:[1,0,1]
	v_lshlrev_b32_e32 v158, 16, v160
	v_and_b32_e32 v159, 0xffff0000, v160
	v_pk_fma_f32 v[202:203], v[58:59], 0.5, v[158:159] op_sel_hi:[1,0,1]
	v_lshlrev_b32_e32 v158, 16, v161
	v_and_b32_e32 v159, 0xffff0000, v161
	v_pk_fma_f32 v[190:191], v[62:63], 0.5, v[190:191] op_sel_hi:[1,0,1]
	v_pk_fma_f32 v[204:205], v[60:61], 0.5, v[158:159] op_sel_hi:[1,0,1]
	v_cvt_pk_bf16_f32 v158, v190, v191
	v_cvt_pk_bf16_f32 v159, v192, v193
	v_cvt_pk_bf16_f32 v160, v202, v203
	v_cvt_pk_bf16_f32 v161, v204, v205
	s_cbranch_vccnz .LBB0_427
	s_mov_b64 s[54:55], 0
	global_store_dwordx4 v[172:173], v[158:161], off offset:-4096

.LBB0_429:
	v_lshlrev_b32_e32 v160, 16, v154
	v_and_b32_e32 v161, 0xffff0000, v154
	v_lshlrev_b32_e32 v154, 16, v155
	v_and_b32_e32 v155, 0xffff0000, v155
	v_pk_fma_f32 v[188:189], v[32:33], 0.5, v[154:155] op_sel_hi:[1,0,1]
	v_lshlrev_b32_e32 v154, 16, v156
	v_and_b32_e32 v155, 0xffff0000, v156
	v_pk_fma_f32 v[206:207], v[26:27], 0.5, v[154:155] op_sel_hi:[1,0,1]
	v_lshlrev_b32_e32 v154, 16, v157
	v_and_b32_e32 v155, 0xffff0000, v157
	v_pk_fma_f32 v[160:161], v[30:31], 0.5, v[160:161] op_sel_hi:[1,0,1]
	v_pk_fma_f32 v[208:209], v[28:29], 0.5, v[154:155] op_sel_hi:[1,0,1]
	v_cvt_pk_bf16_f32 v154, v160, v161
	v_cvt_pk_bf16_f32 v155, v188, v189
	v_cvt_pk_bf16_f32 v156, v206, v207
	v_cvt_pk_bf16_f32 v157, v208, v209
	s_and_b64 vcc, exec, s[12:13]
	s_mov_b64 s[54:55], -1
	s_cbranch_vccnz .LBB0_431
	s_mov_b64 s[54:55], 0
	global_store_dwordx4 v[174:175], v[154:157], off offset:-4096

.LBB0_439:
	s_or_b64 exec, exec, s[54:55]
	s_waitcnt lgkmcnt(0)
	v_lshlrev_b32_e32 v154, 16, v150
	v_and_b32_e32 v155, 0xffff0000, v150
	v_lshlrev_b32_e32 v150, 16, v151
	v_and_b32_e32 v151, 0xffff0000, v151
	v_pk_fma_f32 v[156:157], v[56:57], 0.5, v[150:151] op_sel_hi:[1,0,1]
	v_lshlrev_b32_e32 v150, 16, v152
	v_and_b32_e32 v151, 0xffff0000, v152
	v_pk_fma_f32 v[158:159], v[50:51], 0.5, v[150:151] op_sel_hi:[1,0,1]
	v_lshlrev_b32_e32 v150, 16, v153
	v_and_b32_e32 v151, 0xffff0000, v153
	v_pk_fma_f32 v[154:155], v[54:55], 0.5, v[154:155] op_sel_hi:[1,0,1]
	v_pk_fma_f32 v[160:161], v[52:53], 0.5, v[150:151] op_sel_hi:[1,0,1]
	v_cvt_pk_bf16_f32 v150, v154, v155
	v_cvt_pk_bf16_f32 v151, v156, v157
	v_cvt_pk_bf16_f32 v152, v158, v159
	v_cvt_pk_bf16_f32 v153, v160, v161
	s_nor_b64 s[54:55], s[62:63], s[50:51]
	s_and_saveexec_b64 s[62:63], s[54:55]
	s_xor_b64 s[54:55], exec, s[62:63]
	s_cbranch_execz .LBB0_441
	global_store_dwordx4 v[172:173], v[150:153], off offset:-2048

.LBB0_443:
	s_or_b64 exec, exec, s[54:55]
	s_nop 0
	v_lshlrev_b32_e32 v152, 16, v146
	v_and_b32_e32 v153, 0xffff0000, v146
	v_lshlrev_b32_e32 v146, 16, v147
	v_and_b32_e32 v147, 0xffff0000, v147
	v_pk_fma_f32 v[180:181], v[24:25], 0.5, v[146:147] op_sel_hi:[1,0,1]
	v_lshlrev_b32_e32 v146, 16, v148
	v_and_b32_e32 v147, 0xffff0000, v148
	v_pk_fma_f32 v[182:183], v[18:19], 0.5, v[146:147] op_sel_hi:[1,0,1]
	v_lshlrev_b32_e32 v146, 16, v149
	v_and_b32_e32 v147, 0xffff0000, v149
	v_pk_fma_f32 v[152:153], v[22:23], 0.5, v[152:153] op_sel_hi:[1,0,1]
	v_pk_fma_f32 v[184:185], v[20:21], 0.5, v[146:147] op_sel_hi:[1,0,1]
	v_cvt_pk_bf16_f32 v146, v152, v153
	v_cvt_pk_bf16_f32 v147, v180, v181
	v_cvt_pk_bf16_f32 v148, v182, v183
	v_cvt_pk_bf16_f32 v149, v184, v185
	s_and_b64 vcc, exec, s[12:13]
	s_mov_b64 s[54:55], -1
	s_cbranch_vccnz .LBB0_445
	s_mov_b64 s[54:55], 0
	global_store_dwordx4 v[174:175], v[146:149], off offset:-2048

.LBB0_453:
	s_or_b64 exec, exec, s[54:55]
	s_waitcnt lgkmcnt(0)
	v_lshlrev_b32_e32 v146, 16, v142
	v_and_b32_e32 v147, 0xffff0000, v142
	v_lshlrev_b32_e32 v142, 16, v143
	v_and_b32_e32 v143, 0xffff0000, v143
	v_pk_fma_f32 v[148:149], v[48:49], 0.5, v[142:143] op_sel_hi:[1,0,1]
	v_lshlrev_b32_e32 v142, 16, v144
	v_and_b32_e32 v143, 0xffff0000, v144
	v_pk_fma_f32 v[150:151], v[42:43], 0.5, v[142:143] op_sel_hi:[1,0,1]
	v_lshlrev_b32_e32 v142, 16, v145
	v_and_b32_e32 v143, 0xffff0000, v145
	v_pk_fma_f32 v[146:147], v[46:47], 0.5, v[146:147] op_sel_hi:[1,0,1]
	v_pk_fma_f32 v[152:153], v[44:45], 0.5, v[142:143] op_sel_hi:[1,0,1]
	v_cvt_pk_bf16_f32 v142, v146, v147
	v_cvt_pk_bf16_f32 v143, v148, v149
	v_cvt_pk_bf16_f32 v144, v150, v151
	v_cvt_pk_bf16_f32 v145, v152, v153
	s_nor_b64 s[54:55], s[62:63], s[50:51]
	s_and_saveexec_b64 s[62:63], s[54:55]
	s_xor_b64 s[54:55], exec, s[62:63]
	s_cbranch_execz .LBB0_455
	global_store_dwordx4 v[172:173], v[142:145], off

.LBB0_457:
	s_or_b64 exec, exec, s[54:55]
	v_lshlrev_b32_e32 v144, 16, v138
	v_and_b32_e32 v145, 0xffff0000, v138
	v_lshlrev_b32_e32 v138, 16, v139
	v_and_b32_e32 v139, 0xffff0000, v139
	v_pk_fma_f32 v[154:155], v[16:17], 0.5, v[138:139] op_sel_hi:[1,0,1]
	v_lshlrev_b32_e32 v138, 16, v140
	v_and_b32_e32 v139, 0xffff0000, v140
	v_pk_fma_f32 v[156:157], v[10:11], 0.5, v[138:139] op_sel_hi:[1,0,1]
	v_lshlrev_b32_e32 v138, 16, v141
	v_and_b32_e32 v139, 0xffff0000, v141
	v_pk_fma_f32 v[144:145], v[14:15], 0.5, v[144:145] op_sel_hi:[1,0,1]
	v_pk_fma_f32 v[158:159], v[12:13], 0.5, v[138:139] op_sel_hi:[1,0,1]
	v_cvt_pk_bf16_f32 v138, v144, v145
	v_cvt_pk_bf16_f32 v139, v154, v155
	v_cvt_pk_bf16_f32 v140, v156, v157
	v_cvt_pk_bf16_f32 v141, v158, v159
	s_and_b64 vcc, exec, s[12:13]
	s_mov_b64 s[54:55], -1
	s_cbranch_vccnz .LBB0_459
	s_mov_b64 s[54:55], 0
	global_store_dwordx4 v[174:175], v[138:141], off

.LBB0_467:
	s_or_b64 exec, exec, s[54:55]
	s_waitcnt lgkmcnt(0)
	v_lshlrev_b32_e32 v138, 16, v134
	v_and_b32_e32 v139, 0xffff0000, v134
	v_lshlrev_b32_e32 v134, 16, v135
	v_and_b32_e32 v135, 0xffff0000, v135
	v_pk_fma_f32 v[140:141], v[40:41], 0.5, v[134:135] op_sel_hi:[1,0,1]
	v_lshlrev_b32_e32 v134, 16, v136
	v_and_b32_e32 v135, 0xffff0000, v136
	v_pk_fma_f32 v[142:143], v[34:35], 0.5, v[134:135] op_sel_hi:[1,0,1]
	v_lshlrev_b32_e32 v134, 16, v137
	v_and_b32_e32 v135, 0xffff0000, v137
	v_pk_fma_f32 v[138:139], v[38:39], 0.5, v[138:139] op_sel_hi:[1,0,1]
	v_pk_fma_f32 v[144:145], v[36:37], 0.5, v[134:135] op_sel_hi:[1,0,1]
	v_cvt_pk_bf16_f32 v134, v138, v139
	v_cvt_pk_bf16_f32 v135, v140, v141
	v_cvt_pk_bf16_f32 v136, v142, v143
	v_cvt_pk_bf16_f32 v137, v144, v145
	s_nor_b64 s[50:51], s[62:63], s[50:51]
	s_and_saveexec_b64 s[54:55], s[50:51]
	s_xor_b64 s[50:51], exec, s[54:55]
	s_cbranch_execz .LBB0_469
	global_store_dwordx4 v[172:173], v[134:137], off offset:2048

.LBB0_471:
	s_or_b64 exec, exec, s[50:51]
	v_lshlrev_b32_e32 v136, 16, v130
	v_and_b32_e32 v137, 0xffff0000, v130
	v_lshlrev_b32_e32 v130, 16, v131
	v_and_b32_e32 v131, 0xffff0000, v131
	v_pk_fma_f32 v[146:147], v[8:9], 0.5, v[130:131] op_sel_hi:[1,0,1]
	v_lshlrev_b32_e32 v130, 16, v132
	v_and_b32_e32 v131, 0xffff0000, v132
	v_pk_fma_f32 v[148:149], v[2:3], 0.5, v[130:131] op_sel_hi:[1,0,1]
	v_lshlrev_b32_e32 v130, 16, v133
	v_and_b32_e32 v131, 0xffff0000, v133
	v_pk_fma_f32 v[136:137], v[6:7], 0.5, v[136:137] op_sel_hi:[1,0,1]
	v_pk_fma_f32 v[150:151], v[4:5], 0.5, v[130:131] op_sel_hi:[1,0,1]
	v_cvt_pk_bf16_f32 v130, v136, v137
	v_cvt_pk_bf16_f32 v131, v146, v147
	v_cvt_pk_bf16_f32 v132, v148, v149
	v_cvt_pk_bf16_f32 v133, v150, v151
	s_and_b64 vcc, exec, s[12:13]
	s_mov_b64 s[50:51], -1
	s_cbranch_vccnz .LBB0_473
	s_mov_b64 s[50:51], 0
	global_store_dwordx4 v[174:175], v[130:133], off offset:2048

.LBB0_1529:
	s_nop 0
	s_nop 0
	s_mov_b32 s98, 0x5000
	s_mov_b32 s99, 0x0
	v_lshl_add_u64 v[240:241], v[166:167], 0, s[98:99]
	s_mov_b32 s98, 0x15000
	s_mov_b32 s99, 0x0
	v_lshl_add_u64 v[242:243], v[166:167], 0, s[98:99]
	global_load_dwordx4 v[122:125], v[240:241], off offset:-4096
	global_load_dwordx4 v[126:129], v[242:243], off offset:-4096
	s_waitcnt vmcnt(8)
	v_lshlrev_b32_e32 v158, 16, v154
	v_and_b32_e32 v159, 0xffff0000, v154
	v_lshlrev_b32_e32 v154, 16, v155
	v_and_b32_e32 v155, 0xffff0000, v155
	v_pk_add_f32 v[160:161], v[96:97], v[154:155]
	v_lshlrev_b32_e32 v154, 16, v156
	v_and_b32_e32 v155, 0xffff0000, v156
	v_pk_add_f32 v[206:207], v[90:91], v[154:155]
	v_lshlrev_b32_e32 v154, 16, v157
	v_and_b32_e32 v155, 0xffff0000, v157
	v_pk_add_f32 v[158:159], v[94:95], v[158:159]
	v_pk_add_f32 v[208:209], v[92:93], v[154:155]
	v_cndmask_b32_e64 v165, 0, 1, s[54:55]
	v_cvt_pk_bf16_f32 v154, v158, v159
	v_cvt_pk_bf16_f32 v155, v160, v161
	v_cvt_pk_bf16_f32 v156, v206, v207
	v_cvt_pk_bf16_f32 v157, v208, v209
	v_cmp_ne_u32_e64 s[10:11], 1, v165
	s_andn2_b64 vcc, exec, s[54:55]
	s_mov_b64 s[12:13], -1
	s_cbranch_vccnz .LBB0_1531
	s_mov_b64 s[12:13], 0
	global_store_dwordx4 v[172:173], v[154:157], off offset:-4096

.LBB0_1539:
	s_or_b64 exec, exec, s[56:57]
	s_waitcnt lgkmcnt(0)
	global_load_dwordx4 v[90:93], v[240:241], off offset:-2048
	global_load_dwordx4 v[94:97], v[242:243], off offset:-2048
	s_waitcnt vmcnt(9)
	v_lshlrev_b32_e32 v154, 16, v150
	v_and_b32_e32 v155, 0xffff0000, v150
	v_lshlrev_b32_e32 v150, 16, v151
	v_and_b32_e32 v151, 0xffff0000, v151
	v_pk_add_f32 v[156:157], v[120:121], v[150:151]
	v_lshlrev_b32_e32 v150, 16, v152
	v_and_b32_e32 v151, 0xffff0000, v152
	v_pk_add_f32 v[158:159], v[114:115], v[150:151]
	v_lshlrev_b32_e32 v150, 16, v153
	v_and_b32_e32 v151, 0xffff0000, v153
	v_pk_add_f32 v[154:155], v[118:119], v[154:155]
	v_pk_add_f32 v[160:161], v[116:117], v[150:151]
	v_cvt_pk_bf16_f32 v150, v154, v155
	v_cvt_pk_bf16_f32 v151, v156, v157
	v_cvt_pk_bf16_f32 v152, v158, v159
	v_cvt_pk_bf16_f32 v153, v160, v161
	s_nor_b64 s[54:55], s[58:59], s[50:51]
	s_and_saveexec_b64 s[56:57], s[54:55]
	s_xor_b64 s[54:55], exec, s[56:57]
	s_cbranch_execz .LBB0_1541
	global_store_dwordx4 v[174:175], v[150:153], off offset:-2048

.LBB0_1543:
	s_or_b64 exec, exec, s[54:55]
	s_nop 0
	s_nop 0
	global_load_dwordx4 v[114:117], v[240:241], off
	global_load_dwordx4 v[118:121], v[242:243], off
	s_waitcnt vmcnt(10)
	v_lshlrev_b32_e32 v150, 16, v146
	v_and_b32_e32 v151, 0xffff0000, v146
	v_lshlrev_b32_e32 v146, 16, v147
	v_and_b32_e32 v147, 0xffff0000, v147
	v_pk_add_f32 v[182:183], v[88:89], v[146:147]
	v_lshlrev_b32_e32 v146, 16, v148
	v_and_b32_e32 v147, 0xffff0000, v148
	v_pk_add_f32 v[184:185], v[82:83], v[146:147]
	v_lshlrev_b32_e32 v146, 16, v149
	v_and_b32_e32 v147, 0xffff0000, v149
	v_pk_add_f32 v[150:151], v[86:87], v[150:151]
	v_pk_add_f32 v[186:187], v[84:85], v[146:147]
	v_cvt_pk_bf16_f32 v146, v150, v151
	v_cvt_pk_bf16_f32 v147, v182, v183
	v_cvt_pk_bf16_f32 v148, v184, v185
	v_cvt_pk_bf16_f32 v149, v186, v187
	s_and_b64 vcc, exec, s[10:11]
	s_mov_b64 s[54:55], -1
	s_cbranch_vccnz .LBB0_1545
	s_mov_b64 s[54:55], 0
	global_store_dwordx4 v[172:173], v[146:149], off offset:-2048

.LBB0_1553:
	s_or_b64 exec, exec, s[54:55]
	s_waitcnt lgkmcnt(0)
	global_load_dwordx4 v[82:85], v[240:241], off offset:2048
	global_load_dwordx4 v[86:89], v[242:243], off offset:2048
	s_waitcnt vmcnt(11)
	v_lshlrev_b32_e32 v146, 16, v142
	v_and_b32_e32 v147, 0xffff0000, v142
	v_lshlrev_b32_e32 v142, 16, v143
	v_and_b32_e32 v143, 0xffff0000, v143
	v_pk_add_f32 v[148:149], v[112:113], v[142:143]
	v_lshlrev_b32_e32 v142, 16, v144
	v_and_b32_e32 v143, 0xffff0000, v144
	v_pk_add_f32 v[150:151], v[106:107], v[142:143]
	v_lshlrev_b32_e32 v142, 16, v145
	v_and_b32_e32 v143, 0xffff0000, v145
	v_pk_add_f32 v[146:147], v[110:111], v[146:147]
	v_pk_add_f32 v[152:153], v[108:109], v[142:143]
	v_cvt_pk_bf16_f32 v142, v146, v147
	v_cvt_pk_bf16_f32 v143, v148, v149
	v_cvt_pk_bf16_f32 v144, v150, v151
	v_cvt_pk_bf16_f32 v145, v152, v153
	s_nor_b64 s[54:55], s[56:57], s[50:51]
	s_and_saveexec_b64 s[56:57], s[54:55]
	s_xor_b64 s[54:55], exec, s[56:57]
	s_cbranch_execz .LBB0_1555
	global_store_dwordx4 v[174:175], v[142:145], off

.LBB0_1557:
	s_or_b64 exec, exec, s[54:55]
	s_nop 0
	s_nop 0
	s_waitcnt vmcnt(10)
	v_lshlrev_b32_e32 v142, 16, v138
	v_and_b32_e32 v143, 0xffff0000, v138
	v_lshlrev_b32_e32 v138, 16, v139
	v_and_b32_e32 v139, 0xffff0000, v139
	v_pk_add_f32 v[154:155], v[80:81], v[138:139]
	v_lshlrev_b32_e32 v138, 16, v140
	v_and_b32_e32 v139, 0xffff0000, v140
	v_pk_add_f32 v[156:157], v[74:75], v[138:139]
	v_lshlrev_b32_e32 v138, 16, v141
	v_and_b32_e32 v139, 0xffff0000, v141
	v_pk_add_f32 v[142:143], v[78:79], v[142:143]
	v_pk_add_f32 v[158:159], v[76:77], v[138:139]
	v_cvt_pk_bf16_f32 v138, v142, v143
	v_cvt_pk_bf16_f32 v139, v154, v155
	v_cvt_pk_bf16_f32 v140, v156, v157
	v_cvt_pk_bf16_f32 v141, v158, v159
	s_and_b64 vcc, exec, s[10:11]
	s_mov_b64 s[54:55], -1
	s_cbranch_vccnz .LBB0_1559
	s_mov_b64 s[54:55], 0
	global_store_dwordx4 v[172:173], v[138:141], off

.LBB0_1567:
	s_or_b64 exec, exec, s[54:55]
	s_waitcnt lgkmcnt(0)
	s_waitcnt vmcnt(9)
	v_lshlrev_b32_e32 v138, 16, v134
	v_and_b32_e32 v139, 0xffff0000, v134
	v_lshlrev_b32_e32 v134, 16, v135
	v_and_b32_e32 v135, 0xffff0000, v135
	v_pk_add_f32 v[140:141], v[104:105], v[134:135]
	v_lshlrev_b32_e32 v134, 16, v136
	v_and_b32_e32 v135, 0xffff0000, v136
	v_pk_add_f32 v[142:143], v[98:99], v[134:135]
	v_lshlrev_b32_e32 v134, 16, v137
	v_and_b32_e32 v135, 0xffff0000, v137
	v_pk_add_f32 v[138:139], v[102:103], v[138:139]
	v_pk_add_f32 v[144:145], v[100:101], v[134:135]
	v_cvt_pk_bf16_f32 v134, v138, v139
	v_cvt_pk_bf16_f32 v135, v140, v141
	v_cvt_pk_bf16_f32 v136, v142, v143
	v_cvt_pk_bf16_f32 v137, v144, v145
	s_nor_b64 s[54:55], s[56:57], s[50:51]
	s_and_saveexec_b64 s[56:57], s[54:55]
	s_xor_b64 s[54:55], exec, s[56:57]
	s_cbranch_execz .LBB0_1569
	global_store_dwordx4 v[174:175], v[134:137], off offset:2048

.LBB0_1571:
	s_or_b64 exec, exec, s[54:55]
	s_nop 0
	s_nop 0
	s_waitcnt vmcnt(8)
	v_lshlrev_b32_e32 v134, 16, v130
	v_and_b32_e32 v135, 0xffff0000, v130
	v_lshlrev_b32_e32 v130, 16, v131
	v_and_b32_e32 v131, 0xffff0000, v131
	v_pk_add_f32 v[146:147], v[72:73], v[130:131]
	v_lshlrev_b32_e32 v130, 16, v132
	v_and_b32_e32 v131, 0xffff0000, v132
	v_pk_add_f32 v[148:149], v[66:67], v[130:131]
	v_lshlrev_b32_e32 v130, 16, v133
	v_and_b32_e32 v131, 0xffff0000, v133
	v_pk_add_f32 v[134:135], v[70:71], v[134:135]
	v_pk_add_f32 v[150:151], v[68:69], v[130:131]
	v_cvt_pk_bf16_f32 v130, v134, v135
	v_cvt_pk_bf16_f32 v131, v146, v147
	v_cvt_pk_bf16_f32 v132, v148, v149
	v_cvt_pk_bf16_f32 v133, v150, v151
	s_and_b64 vcc, exec, s[10:11]
	s_mov_b64 s[54:55], -1
	s_cbranch_vccnz .LBB0_1573
	s_mov_b64 s[54:55], 0
	global_store_dwordx4 v[172:173], v[130:133], off offset:2048

.LBB0_1580:
	s_or_b64 exec, exec, s[54:55]
	v_add_u32_e32 v184, 0x80, v162
	s_waitcnt lgkmcnt(0)
	v_lshlrev_b32_e32 v131, 6, v184
	v_lshlrev_b32_e32 v132, 2, v184
	v_lshlrev_b32_e32 v130, 7, v184
	v_and_b32_e32 v131, 0x3c0, v131
	v_and_b32_e32 v132, 32, v132
	v_and_b32_e32 v130, 0x4000, v130
	v_bitop3_b32 v131, v131, v132, v221 bitop3:0x36
	v_or3_b32 v198, v130, v131, v224
	v_add_u32_e32 v176, 0x90, v162
	s_mov_b32 s98, 0x5000
	s_mov_b32 s99, 0x0
	v_lshl_add_u64 v[172:173], v[166:167], 0, s[98:99]
	s_waitcnt vmcnt(4)
	v_mov_b32_e32 v158, v122
	v_mov_b32_e32 v159, v123
	v_mov_b32_e32 v160, v124
	v_mov_b32_e32 v161, v125
	s_mov_b32 s98, 0x15000
	s_mov_b32 s99, 0x0
	v_lshl_add_u64 v[174:175], v[166:167], 0, s[98:99]
	v_mov_b32_e32 v154, v126
	v_mov_b32_e32 v155, v127
	v_mov_b32_e32 v156, v128
	v_mov_b32_e32 v157, v129
	v_add_u32_e32 v168, 0xa0, v162
	v_mov_b32_e32 v150, v90
	v_mov_b32_e32 v151, v91
	v_mov_b32_e32 v152, v92
	v_mov_b32_e32 v153, v93
	v_mov_b32_e32 v146, v94
	v_mov_b32_e32 v147, v95
	v_mov_b32_e32 v148, v96
	v_mov_b32_e32 v149, v97
	v_add_u32_e32 v162, 0xb0, v162
	v_mov_b32_e32 v142, v114
	v_mov_b32_e32 v143, v115
	v_mov_b32_e32 v144, v116
	v_mov_b32_e32 v145, v117
	v_mov_b32_e32 v138, v118
	v_mov_b32_e32 v139, v119
	v_mov_b32_e32 v140, v120
	v_mov_b32_e32 v141, v121
	v_mov_b32_e32 v134, v82
	v_mov_b32_e32 v135, v83
	v_mov_b32_e32 v136, v84
	v_mov_b32_e32 v137, v85
	s_nop 0
	v_mov_b32_e32 v130, v86
	v_mov_b32_e32 v131, v87
	v_mov_b32_e32 v132, v88
	v_mov_b32_e32 v133, v89
	s_and_b64 vcc, exec, s[10:11]
	s_mov_b64 s[54:55], -1
	v_lshlrev_b32_e32 v190, 16, v158
	v_and_b32_e32 v191, 0xffff0000, v158
	v_lshlrev_b32_e32 v158, 16, v159
	v_and_b32_e32 v159, 0xffff0000, v159
	v_pk_add_f32 v[192:193], v[64:65], v[158:159]
	v_lshlrev_b32_e32 v158, 16, v160
	v_and_b32_e32 v159, 0xffff0000, v160
	v_pk_add_f32 v[202:203], v[58:59], v[158:159]
	v_lshlrev_b32_e32 v158, 16, v161
	v_and_b32_e32 v159, 0xffff0000, v161
	v_pk_add_f32 v[190:191], v[62:63], v[190:191]
	v_pk_add_f32 v[204:205], v[60:61], v[158:159]
	v_cvt_pk_bf16_f32 v158, v190, v191
	v_cvt_pk_bf16_f32 v159, v192, v193
	v_cvt_pk_bf16_f32 v160, v202, v203
	v_cvt_pk_bf16_f32 v161, v204, v205
	s_cbranch_vccnz .LBB0_1582
	s_mov_b64 s[54:55], 0
	global_store_dwordx4 v[172:173], v[158:161], off offset:-4096

.LBB0_1584:
	s_nop 0
	s_nop 0
	v_lshlrev_b32_e32 v158, 16, v154
	v_and_b32_e32 v159, 0xffff0000, v154
	v_lshlrev_b32_e32 v154, 16, v155
	v_and_b32_e32 v155, 0xffff0000, v155
	v_pk_add_f32 v[188:189], v[32:33], v[154:155]
	v_lshlrev_b32_e32 v154, 16, v156
	v_and_b32_e32 v155, 0xffff0000, v156
	v_pk_add_f32 v[206:207], v[26:27], v[154:155]
	v_lshlrev_b32_e32 v154, 16, v157
	v_and_b32_e32 v155, 0xffff0000, v157
	v_pk_add_f32 v[158:159], v[30:31], v[158:159]
	v_pk_add_f32 v[208:209], v[28:29], v[154:155]
	v_cvt_pk_bf16_f32 v154, v158, v159
	v_cvt_pk_bf16_f32 v155, v188, v189
	v_cvt_pk_bf16_f32 v156, v206, v207
	v_cvt_pk_bf16_f32 v157, v208, v209
	s_and_b64 vcc, exec, s[10:11]
	s_mov_b64 s[54:55], -1
	s_cbranch_vccnz .LBB0_1586
	s_mov_b64 s[54:55], 0
	global_store_dwordx4 v[174:175], v[154:157], off offset:-4096

.LBB0_1594:
	s_or_b64 exec, exec, s[54:55]
	s_waitcnt lgkmcnt(0)
	v_lshlrev_b32_e32 v154, 16, v150
	v_and_b32_e32 v155, 0xffff0000, v150
	v_lshlrev_b32_e32 v150, 16, v151
	v_and_b32_e32 v151, 0xffff0000, v151
	v_pk_add_f32 v[156:157], v[56:57], v[150:151]
	v_lshlrev_b32_e32 v150, 16, v152
	v_and_b32_e32 v151, 0xffff0000, v152
	v_pk_add_f32 v[158:159], v[50:51], v[150:151]
	v_lshlrev_b32_e32 v150, 16, v153
	v_and_b32_e32 v151, 0xffff0000, v153
	v_pk_add_f32 v[154:155], v[54:55], v[154:155]
	v_pk_add_f32 v[160:161], v[52:53], v[150:151]
	v_cvt_pk_bf16_f32 v150, v154, v155
	v_cvt_pk_bf16_f32 v151, v156, v157
	v_cvt_pk_bf16_f32 v152, v158, v159
	v_cvt_pk_bf16_f32 v153, v160, v161
	s_nor_b64 s[54:55], s[56:57], s[50:51]
	s_and_saveexec_b64 s[56:57], s[54:55]
	s_xor_b64 s[54:55], exec, s[56:57]
	s_cbranch_execz .LBB0_1596
	global_store_dwordx4 v[172:173], v[150:153], off offset:-2048

.LBB0_1598:
	s_or_b64 exec, exec, s[54:55]
	s_nop 0
	s_nop 0
	v_lshlrev_b32_e32 v150, 16, v146
	v_and_b32_e32 v151, 0xffff0000, v146
	v_lshlrev_b32_e32 v146, 16, v147
	v_and_b32_e32 v147, 0xffff0000, v147
	v_pk_add_f32 v[180:181], v[24:25], v[146:147]
	v_lshlrev_b32_e32 v146, 16, v148
	v_and_b32_e32 v147, 0xffff0000, v148
	v_pk_add_f32 v[182:183], v[18:19], v[146:147]
	v_lshlrev_b32_e32 v146, 16, v149
	v_and_b32_e32 v147, 0xffff0000, v149
	v_pk_add_f32 v[150:151], v[22:23], v[150:151]
	v_pk_add_f32 v[184:185], v[20:21], v[146:147]
	v_cvt_pk_bf16_f32 v146, v150, v151
	v_cvt_pk_bf16_f32 v147, v180, v181
	v_cvt_pk_bf16_f32 v148, v182, v183
	v_cvt_pk_bf16_f32 v149, v184, v185
	s_and_b64 vcc, exec, s[10:11]
	s_mov_b64 s[54:55], -1
	s_cbranch_vccnz .LBB0_1600
	s_mov_b64 s[54:55], 0
	global_store_dwordx4 v[174:175], v[146:149], off offset:-2048

.LBB0_1608:
	s_or_b64 exec, exec, s[54:55]
	s_waitcnt lgkmcnt(0)
	v_lshlrev_b32_e32 v146, 16, v142
	v_and_b32_e32 v147, 0xffff0000, v142
	v_lshlrev_b32_e32 v142, 16, v143
	v_and_b32_e32 v143, 0xffff0000, v143
	v_pk_add_f32 v[148:149], v[48:49], v[142:143]
	v_lshlrev_b32_e32 v142, 16, v144
	v_and_b32_e32 v143, 0xffff0000, v144
	v_pk_add_f32 v[150:151], v[42:43], v[142:143]
	v_lshlrev_b32_e32 v142, 16, v145
	v_and_b32_e32 v143, 0xffff0000, v145
	v_pk_add_f32 v[146:147], v[46:47], v[146:147]
	v_pk_add_f32 v[152:153], v[44:45], v[142:143]
	v_cvt_pk_bf16_f32 v142, v146, v147
	v_cvt_pk_bf16_f32 v143, v148, v149
	v_cvt_pk_bf16_f32 v144, v150, v151
	v_cvt_pk_bf16_f32 v145, v152, v153
	s_nor_b64 s[54:55], s[56:57], s[50:51]
	s_and_saveexec_b64 s[56:57], s[54:55]
	s_xor_b64 s[54:55], exec, s[56:57]
	s_cbranch_execz .LBB0_1610
	global_store_dwordx4 v[172:173], v[142:145], off

.LBB0_1612:
	s_or_b64 exec, exec, s[54:55]
	s_nop 0
	s_nop 0
	v_lshlrev_b32_e32 v142, 16, v138
	v_and_b32_e32 v143, 0xffff0000, v138
	v_lshlrev_b32_e32 v138, 16, v139
	v_and_b32_e32 v139, 0xffff0000, v139
	v_pk_add_f32 v[154:155], v[16:17], v[138:139]
	v_lshlrev_b32_e32 v138, 16, v140
	v_and_b32_e32 v139, 0xffff0000, v140
	v_pk_add_f32 v[156:157], v[10:11], v[138:139]
	v_lshlrev_b32_e32 v138, 16, v141
	v_and_b32_e32 v139, 0xffff0000, v141
	v_pk_add_f32 v[142:143], v[14:15], v[142:143]
	v_pk_add_f32 v[158:159], v[12:13], v[138:139]
	v_cvt_pk_bf16_f32 v138, v142, v143
	v_cvt_pk_bf16_f32 v139, v154, v155
	v_cvt_pk_bf16_f32 v140, v156, v157
	v_cvt_pk_bf16_f32 v141, v158, v159
	s_and_b64 vcc, exec, s[10:11]
	s_mov_b64 s[54:55], -1
	s_cbranch_vccnz .LBB0_1614
	s_mov_b64 s[54:55], 0
	global_store_dwordx4 v[174:175], v[138:141], off

.LBB0_1622:
	s_or_b64 exec, exec, s[54:55]
	s_waitcnt lgkmcnt(0)
	v_lshlrev_b32_e32 v138, 16, v134
	v_and_b32_e32 v139, 0xffff0000, v134
	v_lshlrev_b32_e32 v134, 16, v135
	v_and_b32_e32 v135, 0xffff0000, v135
	v_pk_add_f32 v[140:141], v[40:41], v[134:135]
	v_lshlrev_b32_e32 v134, 16, v136
	v_and_b32_e32 v135, 0xffff0000, v136
	v_pk_add_f32 v[142:143], v[34:35], v[134:135]
	v_lshlrev_b32_e32 v134, 16, v137
	v_and_b32_e32 v135, 0xffff0000, v137
	v_pk_add_f32 v[138:139], v[38:39], v[138:139]
	v_pk_add_f32 v[144:145], v[36:37], v[134:135]
	v_cvt_pk_bf16_f32 v134, v138, v139
	v_cvt_pk_bf16_f32 v135, v140, v141
	v_cvt_pk_bf16_f32 v136, v142, v143
	v_cvt_pk_bf16_f32 v137, v144, v145
	s_nor_b64 s[50:51], s[56:57], s[50:51]
	s_and_saveexec_b64 s[54:55], s[50:51]
	s_xor_b64 s[50:51], exec, s[54:55]
	s_cbranch_execz .LBB0_1624
	global_store_dwordx4 v[172:173], v[134:137], off offset:2048

.LBB0_1626:
	s_or_b64 exec, exec, s[50:51]
	s_nop 0
	s_nop 0
	v_lshlrev_b32_e32 v134, 16, v130
	v_and_b32_e32 v135, 0xffff0000, v130
	v_lshlrev_b32_e32 v130, 16, v131
	v_and_b32_e32 v131, 0xffff0000, v131
	v_pk_add_f32 v[146:147], v[8:9], v[130:131]
	v_lshlrev_b32_e32 v130, 16, v132
	v_and_b32_e32 v131, 0xffff0000, v132
	v_pk_add_f32 v[148:149], v[2:3], v[130:131]
	v_lshlrev_b32_e32 v130, 16, v133
	v_and_b32_e32 v131, 0xffff0000, v133
	v_pk_add_f32 v[134:135], v[6:7], v[134:135]
	v_pk_add_f32 v[150:151], v[4:5], v[130:131]
	v_cvt_pk_bf16_f32 v130, v134, v135
	v_cvt_pk_bf16_f32 v131, v146, v147
	v_cvt_pk_bf16_f32 v132, v148, v149
	v_cvt_pk_bf16_f32 v133, v150, v151
	s_and_b64 vcc, exec, s[10:11]
	s_mov_b64 s[50:51], -1
	s_cbranch_vccnz .LBB0_1628
	s_mov_b64 s[50:51], 0
	global_store_dwordx4 v[174:175], v[130:133], off offset:2048

.LBB0_1924:
	s_lshl_b32 s6, s72, 8
	v_mov_b32_e32 v114, v200
	v_mov_b32_e32 v163, v210
	s_add_i32 s6, s6, s60
	v_add_u32_e32 v162, s6, v114
	s_lshl_b32 s6, s12, 8
	s_or_b32 s6, s6, s61
	v_lshl_add_u32 v134, v163, 3, s6
	v_bfe_u32 v212, v134, 5, 1
	v_lshrrev_b32_e32 v115, 3, v162
	v_lshlrev_b32_e32 v114, 1, v134
	v_and_or_b32 v115, v115, 14, v212
	v_and_b32_e32 v209, 48, v114
	v_ashrrev_i32_e32 v208, 6, v134
	v_ashrrev_i32_e32 v114, 4, v162
	v_lshlrev_b32_e32 v116, 6, v162
	v_lshlrev_b32_e32 v214, 10, v115
	v_lshlrev_b32_e32 v115, 2, v162
	v_add_u32_e32 v134, 0x80, v134
	v_and_b32_e32 v135, -16, v114
	v_lshlrev_b32_e32 v114, 7, v162
	v_and_b32_e32 v116, 0x3c0, v116
	v_and_b32_e32 v115, 32, v115
	v_ashrrev_i32_e32 v213, 6, v134
	v_and_b32_e32 v114, 0x4000, v114
	v_bitop3_b32 v115, v209, v115, v116 bitop3:0x36
	v_add_u32_e32 v116, v208, v135
	v_or3_b32 v158, v114, v115, v214
	v_ashrrev_i32_e32 v117, 31, v116
	v_lshl_add_u64 v[114:115], s[34:35], 0, v[158:159]
	v_lshlrev_b64 v[198:199], 15, v[116:117]
	v_lshl_add_u64 v[116:117], v[114:115], 0, v[198:199]
	v_add_u32_e32 v178, 16, v162
	v_lshl_add_u64 v[166:167], v[116:117], 0, 0
	global_load_dwordx4 v[190:193], v[116:117], off
	s_mov_b32 s98, 0x11000
	s_mov_b32 s99, 0x0
	v_lshl_add_u64 v[168:169], v[166:167], 0, s[98:99]
	global_load_dwordx4 v[154:157], v[168:169], off offset:-4096
	v_add_u32_e32 v170, 32, v162
	s_mov_b32 s98, 0x1000
	s_mov_b32 s99, 0x0
	v_lshl_add_u64 v[172:173], v[166:167], 0, s[98:99]
	global_load_dwordx4 v[150:153], v[172:173], off offset:-2048
	global_load_dwordx4 v[146:149], v[168:169], off offset:-2048
	v_add_u32_e32 v164, 48, v162
	global_load_dwordx4 v[142:145], v[172:173], off
	global_load_dwordx4 v[138:141], v[168:169], off
	global_load_dwordx4 v[134:137], v[172:173], off offset:2048
	s_nop 0
	global_load_dwordx4 v[114:117], v[168:169], off offset:2048
	s_mov_b32 s98, 0x5000
	s_mov_b32 s99, 0x0
	v_lshl_add_u64 v[242:243], v[166:167], 0, s[98:99]
	s_mov_b32 s98, 0x15000
	s_mov_b32 s99, 0x0
	v_lshl_add_u64 v[250:251], v[166:167], 0, s[98:99]
	global_load_dwordx4 v[218:221], v[242:243], off offset:-4096
	global_load_dwordx4 v[222:225], v[250:251], off offset:-4096
	global_load_dwordx4 v[226:229], v[242:243], off offset:-2048
	global_load_dwordx4 v[230:233], v[250:251], off offset:-2048
	global_load_dwordx4 v[234:237], v[242:243], off
	global_load_dwordx4 v[238:241], v[250:251], off
	global_load_dwordx4 v[180:183], v[242:243], off offset:2048
	global_load_dwordx4 v[184:187], v[250:251], off offset:2048
	s_cmpk_gt_i32 s72, 0x7f
	s_cselect_b64 s[42:43], -1, 0
	v_lshl_add_u64 v[198:199], s[34:35], 0, v[198:199]
	s_nor_b64 s[46:47], s[36:37], s[42:43]
	v_lshl_add_u64 v[198:199], v[198:199], 0, v[158:159]
	s_waitcnt vmcnt(15)
	v_lshlrev_b32_e32 v216, 16, v190
	v_and_b32_e32 v217, 0xffff0000, v190
	v_lshlrev_b32_e32 v190, 16, v191
	v_and_b32_e32 v191, 0xffff0000, v191
	v_pk_add_f32 v[132:133], v[132:133], v[190:191]
	v_lshlrev_b32_e32 v190, 16, v192
	v_and_b32_e32 v191, 0xffff0000, v192
	v_pk_add_f32 v[190:191], v[126:127], v[190:191]
	v_lshlrev_b32_e32 v126, 16, v193
	v_and_b32_e32 v127, 0xffff0000, v193
	v_pk_add_f32 v[130:131], v[130:131], v[216:217]
	v_pk_add_f32 v[192:193], v[128:129], v[126:127]
	v_cvt_pk_bf16_f32 v126, v130, v131
	v_cvt_pk_bf16_f32 v127, v132, v133
	v_cvt_pk_bf16_f32 v128, v190, v191
	v_cvt_pk_bf16_f32 v129, v192, v193
	s_mov_b64 s[6:7], -1
	s_and_b64 vcc, exec, s[46:47]
	s_cbranch_vccz .LBB0_1926
	global_store_dwordx4 v[172:173], v[126:129], off offset:-4096
	s_mov_b64 s[6:7], 0

.LBB0_1928:
	s_waitcnt vmcnt(14)
	v_lshlrev_b32_e32 v128, 16, v154
	v_and_b32_e32 v129, 0xffff0000, v154
	v_pk_add_f32 v[122:123], v[122:123], v[128:129]
	v_lshlrev_b32_e32 v128, 16, v155
	v_and_b32_e32 v129, 0xffff0000, v155
	v_pk_add_f32 v[124:125], v[124:125], v[128:129]
	v_lshlrev_b32_e32 v128, 16, v156
	v_and_b32_e32 v129, 0xffff0000, v156
	v_pk_add_f32 v[128:129], v[118:119], v[128:129]
	v_lshlrev_b32_e32 v118, 16, v157
	v_and_b32_e32 v119, 0xffff0000, v157
	s_nop 0
	v_pk_add_f32 v[154:155], v[120:121], v[118:119]
	v_cndmask_b32_e64 v156, 0, 1, s[46:47]
	v_cvt_pk_bf16_f32 v118, v122, v123
	v_cvt_pk_bf16_f32 v119, v124, v125
	v_cvt_pk_bf16_f32 v120, v128, v129
	v_cvt_pk_bf16_f32 v121, v154, v155
	v_cmp_ne_u32_e64 s[6:7], 1, v156
	s_andn2_b64 vcc, exec, s[46:47]
	s_mov_b64 s[10:11], -1
	s_cbranch_vccnz .LBB0_1930
	s_mov_b64 s[10:11], 0
	global_store_dwordx4 v[168:169], v[118:121], off offset:-4096

.LBB0_1938:
	s_or_b64 exec, exec, s[48:49]
	s_waitcnt lgkmcnt(0)
	s_waitcnt vmcnt(13)
	v_lshlrev_b32_e32 v118, 16, v150
	v_and_b32_e32 v119, 0xffff0000, v150
	v_pk_add_f32 v[110:111], v[110:111], v[118:119]
	v_lshlrev_b32_e32 v118, 16, v151
	v_and_b32_e32 v119, 0xffff0000, v151
	v_pk_add_f32 v[112:113], v[112:113], v[118:119]
	v_lshlrev_b32_e32 v118, 16, v152
	v_and_b32_e32 v119, 0xffff0000, v152
	v_pk_add_f32 v[118:119], v[106:107], v[118:119]
	v_lshlrev_b32_e32 v106, 16, v153
	v_and_b32_e32 v107, 0xffff0000, v153
	v_pk_add_f32 v[120:121], v[108:109], v[106:107]
	v_cvt_pk_bf16_f32 v106, v110, v111
	v_cvt_pk_bf16_f32 v107, v112, v113
	v_cvt_pk_bf16_f32 v108, v118, v119
	v_cvt_pk_bf16_f32 v109, v120, v121
	s_nor_b64 s[46:47], s[50:51], s[42:43]
	s_and_saveexec_b64 s[48:49], s[46:47]
	s_xor_b64 s[46:47], exec, s[48:49]
	s_cbranch_execz .LBB0_1940
	global_store_dwordx4 v[172:173], v[106:109], off offset:-2048

.LBB0_1942:
	s_or_b64 exec, exec, s[46:47]
	s_waitcnt vmcnt(12)
	v_lshlrev_b32_e32 v108, 16, v146
	v_and_b32_e32 v109, 0xffff0000, v146
	v_pk_add_f32 v[102:103], v[102:103], v[108:109]
	v_lshlrev_b32_e32 v108, 16, v147
	v_and_b32_e32 v109, 0xffff0000, v147
	v_pk_add_f32 v[104:105], v[104:105], v[108:109]
	v_lshlrev_b32_e32 v108, 16, v148
	v_and_b32_e32 v109, 0xffff0000, v148
	v_pk_add_f32 v[108:109], v[98:99], v[108:109]
	v_lshlrev_b32_e32 v98, 16, v149
	v_and_b32_e32 v99, 0xffff0000, v149
	v_pk_add_f32 v[122:123], v[100:101], v[98:99]
	v_cvt_pk_bf16_f32 v98, v102, v103
	v_cvt_pk_bf16_f32 v99, v104, v105
	v_cvt_pk_bf16_f32 v100, v108, v109
	v_cvt_pk_bf16_f32 v101, v122, v123
	s_and_b64 vcc, exec, s[6:7]
	s_mov_b64 s[46:47], -1
	s_cbranch_vccnz .LBB0_1944
	s_mov_b64 s[46:47], 0
	global_store_dwordx4 v[168:169], v[98:101], off offset:-2048

.LBB0_1952:
	s_or_b64 exec, exec, s[46:47]
	s_waitcnt lgkmcnt(0)
	s_waitcnt vmcnt(11)
	v_lshlrev_b32_e32 v98, 16, v142
	v_and_b32_e32 v99, 0xffff0000, v142
	v_pk_add_f32 v[94:95], v[94:95], v[98:99]
	v_lshlrev_b32_e32 v98, 16, v143
	v_and_b32_e32 v99, 0xffff0000, v143
	v_pk_add_f32 v[96:97], v[96:97], v[98:99]
	v_lshlrev_b32_e32 v98, 16, v144
	v_and_b32_e32 v99, 0xffff0000, v144
	v_pk_add_f32 v[98:99], v[90:91], v[98:99]
	v_lshlrev_b32_e32 v90, 16, v145
	v_and_b32_e32 v91, 0xffff0000, v145
	v_pk_add_f32 v[100:101], v[92:93], v[90:91]
	v_cvt_pk_bf16_f32 v90, v94, v95
	v_cvt_pk_bf16_f32 v91, v96, v97
	v_cvt_pk_bf16_f32 v92, v98, v99
	v_cvt_pk_bf16_f32 v93, v100, v101
	s_nor_b64 s[46:47], s[48:49], s[42:43]
	s_and_saveexec_b64 s[48:49], s[46:47]
	s_xor_b64 s[46:47], exec, s[48:49]
	s_cbranch_execz .LBB0_1954
	global_store_dwordx4 v[172:173], v[90:93], off

.LBB0_1956:
	s_or_b64 exec, exec, s[46:47]
	s_waitcnt vmcnt(10)
	v_lshlrev_b32_e32 v92, 16, v138
	v_and_b32_e32 v93, 0xffff0000, v138
	v_pk_add_f32 v[86:87], v[86:87], v[92:93]
	v_lshlrev_b32_e32 v92, 16, v139
	v_and_b32_e32 v93, 0xffff0000, v139
	v_pk_add_f32 v[88:89], v[88:89], v[92:93]
	v_lshlrev_b32_e32 v92, 16, v140
	v_and_b32_e32 v93, 0xffff0000, v140
	v_pk_add_f32 v[92:93], v[82:83], v[92:93]
	v_lshlrev_b32_e32 v82, 16, v141
	v_and_b32_e32 v83, 0xffff0000, v141
	v_pk_add_f32 v[102:103], v[84:85], v[82:83]
	v_cvt_pk_bf16_f32 v82, v86, v87
	v_cvt_pk_bf16_f32 v83, v88, v89
	v_cvt_pk_bf16_f32 v84, v92, v93
	v_cvt_pk_bf16_f32 v85, v102, v103
	s_and_b64 vcc, exec, s[6:7]
	s_mov_b64 s[46:47], -1
	s_cbranch_vccnz .LBB0_1958
	s_mov_b64 s[46:47], 0
	global_store_dwordx4 v[168:169], v[82:85], off

.LBB0_1966:
	s_or_b64 exec, exec, s[46:47]
	s_waitcnt lgkmcnt(0)
	s_waitcnt vmcnt(9)
	v_lshlrev_b32_e32 v82, 16, v134
	v_and_b32_e32 v83, 0xffff0000, v134
	v_pk_add_f32 v[78:79], v[78:79], v[82:83]
	v_lshlrev_b32_e32 v82, 16, v135
	v_and_b32_e32 v83, 0xffff0000, v135
	v_pk_add_f32 v[80:81], v[80:81], v[82:83]
	v_lshlrev_b32_e32 v82, 16, v136
	v_and_b32_e32 v83, 0xffff0000, v136
	v_pk_add_f32 v[82:83], v[74:75], v[82:83]
	v_lshlrev_b32_e32 v74, 16, v137
	v_and_b32_e32 v75, 0xffff0000, v137
	v_pk_add_f32 v[84:85], v[76:77], v[74:75]
	v_cvt_pk_bf16_f32 v74, v78, v79
	v_cvt_pk_bf16_f32 v75, v80, v81
	v_cvt_pk_bf16_f32 v76, v82, v83
	v_cvt_pk_bf16_f32 v77, v84, v85
	s_nor_b64 s[46:47], s[48:49], s[42:43]
	s_and_saveexec_b64 s[48:49], s[46:47]
	s_xor_b64 s[46:47], exec, s[48:49]
	s_cbranch_execz .LBB0_1968
	global_store_dwordx4 v[172:173], v[74:77], off offset:2048

.LBB0_1970:
	s_or_b64 exec, exec, s[46:47]
	s_waitcnt vmcnt(8)
	v_lshlrev_b32_e32 v76, 16, v114
	v_and_b32_e32 v77, 0xffff0000, v114
	v_pk_add_f32 v[70:71], v[70:71], v[76:77]
	v_lshlrev_b32_e32 v76, 16, v115
	v_and_b32_e32 v77, 0xffff0000, v115
	v_pk_add_f32 v[72:73], v[72:73], v[76:77]
	v_lshlrev_b32_e32 v76, 16, v116
	v_and_b32_e32 v77, 0xffff0000, v116
	v_pk_add_f32 v[76:77], v[66:67], v[76:77]
	v_lshlrev_b32_e32 v66, 16, v117
	v_and_b32_e32 v67, 0xffff0000, v117
	v_pk_add_f32 v[86:87], v[68:69], v[66:67]
	v_cvt_pk_bf16_f32 v66, v70, v71
	v_cvt_pk_bf16_f32 v67, v72, v73
	v_cvt_pk_bf16_f32 v68, v76, v77
	v_cvt_pk_bf16_f32 v69, v86, v87
	s_and_b64 vcc, exec, s[6:7]
	s_mov_b64 s[46:47], -1
	s_cbranch_vccnz .LBB0_1972
	s_mov_b64 s[46:47], 0
	global_store_dwordx4 v[168:169], v[66:69], off offset:2048

.LBB0_1979:
	s_or_b64 exec, exec, s[46:47]
	v_add_u32_e32 v116, 0x80, v162
	s_waitcnt lgkmcnt(0)
	v_lshlrev_b32_e32 v67, 6, v116
	v_lshlrev_b32_e32 v68, 2, v116
	v_lshlrev_b32_e32 v66, 7, v116
	v_and_b32_e32 v67, 0x3c0, v67
	v_and_b32_e32 v68, 32, v68
	v_and_b32_e32 v66, 0x4000, v66
	v_bitop3_b32 v67, v67, v68, v209 bitop3:0x36
	v_or3_b32 v158, v66, v67, v214
	v_add_u32_e32 v108, 0x90, v162
	s_mov_b32 s98, 0x5000
	s_mov_b32 s99, 0x0
	v_lshl_add_u64 v[168:169], v[166:167], 0, s[98:99]
	s_waitcnt vmcnt(8)
	v_mov_b32_e32 v122, v218
	v_mov_b32_e32 v123, v219
	v_mov_b32_e32 v124, v220
	v_mov_b32_e32 v125, v221
	s_mov_b32 s98, 0x15000
	s_mov_b32 s99, 0x0
	v_lshl_add_u64 v[172:173], v[166:167], 0, s[98:99]
	v_mov_b32_e32 v90, v222
	v_mov_b32_e32 v91, v223
	v_mov_b32_e32 v92, v224
	v_mov_b32_e32 v93, v225
	v_ashrrev_i32_e32 v66, 4, v108
	v_and_b32_e32 v70, -16, v66
	v_add_u32_e32 v70, v213, v70
	v_ashrrev_i32_e32 v71, 31, v70
	v_lshlrev_b64 v[114:115], 15, v[70:71]
	v_add_u32_e32 v100, 0xa0, v162
	v_mov_b32_e32 v86, v226
	v_mov_b32_e32 v87, v227
	v_mov_b32_e32 v88, v228
	v_mov_b32_e32 v89, v229
	v_mov_b32_e32 v82, v230
	v_mov_b32_e32 v83, v231
	v_mov_b32_e32 v84, v232
	v_mov_b32_e32 v85, v233
	v_add_u32_e32 v94, 0xb0, v162
	v_mov_b32_e32 v78, v234
	v_mov_b32_e32 v79, v235
	v_mov_b32_e32 v80, v236
	v_mov_b32_e32 v81, v237
	v_mov_b32_e32 v74, v238
	v_mov_b32_e32 v75, v239
	v_mov_b32_e32 v76, v240
	v_mov_b32_e32 v77, v241
	v_mov_b32_e32 v70, v180
	v_mov_b32_e32 v71, v181
	v_mov_b32_e32 v72, v182
	v_mov_b32_e32 v73, v183
	s_nop 0
	v_mov_b32_e32 v66, v184
	v_mov_b32_e32 v67, v185
	v_mov_b32_e32 v68, v186
	v_mov_b32_e32 v69, v187
	s_and_b64 vcc, exec, s[6:7]
	s_mov_b64 s[46:47], -1
	v_lshlrev_b32_e32 v130, 16, v122
	v_and_b32_e32 v131, 0xffff0000, v122
	v_lshlrev_b32_e32 v122, 16, v123
	v_and_b32_e32 v123, 0xffff0000, v123
	v_pk_add_f32 v[64:65], v[64:65], v[122:123]
	v_lshlrev_b32_e32 v122, 16, v124
	v_and_b32_e32 v123, 0xffff0000, v124
	v_pk_add_f32 v[122:123], v[58:59], v[122:123]
	v_lshlrev_b32_e32 v58, 16, v125
	v_and_b32_e32 v59, 0xffff0000, v125
	v_pk_add_f32 v[62:63], v[62:63], v[130:131]
	v_pk_add_f32 v[124:125], v[60:61], v[58:59]
	v_cvt_pk_bf16_f32 v58, v62, v63
	v_cvt_pk_bf16_f32 v59, v64, v65
	v_cvt_pk_bf16_f32 v60, v122, v123
	v_cvt_pk_bf16_f32 v61, v124, v125
	s_cbranch_vccnz .LBB0_1981
	s_mov_b64 s[46:47], 0
	global_store_dwordx4 v[168:169], v[58:61], off offset:-4096

.LBB0_1983:
	v_lshlrev_b32_e32 v60, 16, v90
	v_and_b32_e32 v61, 0xffff0000, v90
	v_pk_add_f32 v[54:55], v[54:55], v[60:61]
	v_lshlrev_b32_e32 v60, 16, v91
	v_and_b32_e32 v61, 0xffff0000, v91
	v_pk_add_f32 v[56:57], v[56:57], v[60:61]
	v_lshlrev_b32_e32 v60, 16, v92
	v_and_b32_e32 v61, 0xffff0000, v92
	v_pk_add_f32 v[60:61], v[50:51], v[60:61]
	v_lshlrev_b32_e32 v50, 16, v93
	v_and_b32_e32 v51, 0xffff0000, v93
	v_pk_add_f32 v[90:91], v[52:53], v[50:51]
	v_cvt_pk_bf16_f32 v50, v54, v55
	v_cvt_pk_bf16_f32 v51, v56, v57
	v_cvt_pk_bf16_f32 v52, v60, v61
	v_cvt_pk_bf16_f32 v53, v90, v91
	s_and_b64 vcc, exec, s[6:7]
	s_mov_b64 s[46:47], -1
	s_cbranch_vccnz .LBB0_1985
	s_mov_b64 s[46:47], 0
	global_store_dwordx4 v[172:173], v[50:53], off offset:-4096

.LBB0_1993:
	s_or_b64 exec, exec, s[46:47]
	s_waitcnt lgkmcnt(0)
	v_lshlrev_b32_e32 v50, 16, v86
	v_and_b32_e32 v51, 0xffff0000, v86
	v_pk_add_f32 v[46:47], v[46:47], v[50:51]
	v_lshlrev_b32_e32 v50, 16, v87
	v_and_b32_e32 v51, 0xffff0000, v87
	v_pk_add_f32 v[48:49], v[48:49], v[50:51]
	v_lshlrev_b32_e32 v50, 16, v88
	v_and_b32_e32 v51, 0xffff0000, v88
	v_pk_add_f32 v[50:51], v[42:43], v[50:51]
	v_lshlrev_b32_e32 v42, 16, v89
	v_and_b32_e32 v43, 0xffff0000, v89
	v_pk_add_f32 v[52:53], v[44:45], v[42:43]
	v_cvt_pk_bf16_f32 v42, v46, v47
	v_cvt_pk_bf16_f32 v43, v48, v49
	v_cvt_pk_bf16_f32 v44, v50, v51
	v_cvt_pk_bf16_f32 v45, v52, v53
	s_nor_b64 s[46:47], s[48:49], s[42:43]
	s_and_saveexec_b64 s[48:49], s[46:47]
	s_xor_b64 s[46:47], exec, s[48:49]
	s_cbranch_execz .LBB0_1995
	global_store_dwordx4 v[168:169], v[42:45], off offset:-2048

.LBB0_1997:
	s_or_b64 exec, exec, s[46:47]
	v_lshlrev_b32_e32 v44, 16, v82
	v_and_b32_e32 v45, 0xffff0000, v82
	v_pk_add_f32 v[38:39], v[38:39], v[44:45]
	v_lshlrev_b32_e32 v44, 16, v83
	v_and_b32_e32 v45, 0xffff0000, v83
	v_pk_add_f32 v[40:41], v[40:41], v[44:45]
	v_lshlrev_b32_e32 v44, 16, v84
	v_and_b32_e32 v45, 0xffff0000, v84
	v_pk_add_f32 v[44:45], v[34:35], v[44:45]
	v_lshlrev_b32_e32 v34, 16, v85
	v_and_b32_e32 v35, 0xffff0000, v85
	v_pk_add_f32 v[54:55], v[36:37], v[34:35]
	v_cvt_pk_bf16_f32 v34, v38, v39
	v_cvt_pk_bf16_f32 v35, v40, v41
	v_cvt_pk_bf16_f32 v36, v44, v45
	v_cvt_pk_bf16_f32 v37, v54, v55
	s_and_b64 vcc, exec, s[6:7]
	s_mov_b64 s[46:47], -1
	s_cbranch_vccnz .LBB0_1999
	s_mov_b64 s[46:47], 0
	global_store_dwordx4 v[172:173], v[34:37], off offset:-2048

.LBB0_2007:
	s_or_b64 exec, exec, s[46:47]
	s_waitcnt lgkmcnt(0)
	v_lshlrev_b32_e32 v34, 16, v78
	v_and_b32_e32 v35, 0xffff0000, v78
	v_pk_add_f32 v[30:31], v[30:31], v[34:35]
	v_lshlrev_b32_e32 v34, 16, v79
	v_and_b32_e32 v35, 0xffff0000, v79
	v_pk_add_f32 v[32:33], v[32:33], v[34:35]
	v_lshlrev_b32_e32 v34, 16, v80
	v_and_b32_e32 v35, 0xffff0000, v80
	v_pk_add_f32 v[34:35], v[26:27], v[34:35]
	v_lshlrev_b32_e32 v26, 16, v81
	v_and_b32_e32 v27, 0xffff0000, v81
	v_pk_add_f32 v[36:37], v[28:29], v[26:27]
	v_cvt_pk_bf16_f32 v26, v30, v31
	v_cvt_pk_bf16_f32 v27, v32, v33
	v_cvt_pk_bf16_f32 v28, v34, v35
	v_cvt_pk_bf16_f32 v29, v36, v37
	s_nor_b64 s[46:47], s[48:49], s[42:43]
	s_and_saveexec_b64 s[48:49], s[46:47]
	s_xor_b64 s[46:47], exec, s[48:49]
	s_cbranch_execz .LBB0_2009
	global_store_dwordx4 v[168:169], v[26:29], off

.LBB0_2011:
	s_or_b64 exec, exec, s[46:47]
	v_lshlrev_b32_e32 v28, 16, v74
	v_and_b32_e32 v29, 0xffff0000, v74
	v_pk_add_f32 v[22:23], v[22:23], v[28:29]
	v_lshlrev_b32_e32 v28, 16, v75
	v_and_b32_e32 v29, 0xffff0000, v75
	v_pk_add_f32 v[24:25], v[24:25], v[28:29]
	v_lshlrev_b32_e32 v28, 16, v76
	v_and_b32_e32 v29, 0xffff0000, v76
	v_pk_add_f32 v[28:29], v[18:19], v[28:29]
	v_lshlrev_b32_e32 v18, 16, v77
	v_and_b32_e32 v19, 0xffff0000, v77
	v_pk_add_f32 v[38:39], v[20:21], v[18:19]
	v_cvt_pk_bf16_f32 v18, v22, v23
	v_cvt_pk_bf16_f32 v19, v24, v25
	v_cvt_pk_bf16_f32 v20, v28, v29
	v_cvt_pk_bf16_f32 v21, v38, v39
	s_and_b64 vcc, exec, s[6:7]
	s_mov_b64 s[46:47], -1
	s_cbranch_vccnz .LBB0_2013
	s_mov_b64 s[46:47], 0
	global_store_dwordx4 v[172:173], v[18:21], off

.LBB0_2021:
	s_or_b64 exec, exec, s[46:47]
	s_waitcnt lgkmcnt(0)
	v_lshlrev_b32_e32 v18, 16, v70
	v_and_b32_e32 v19, 0xffff0000, v70
	v_pk_add_f32 v[14:15], v[14:15], v[18:19]
	v_lshlrev_b32_e32 v18, 16, v71
	v_and_b32_e32 v19, 0xffff0000, v71
	v_pk_add_f32 v[16:17], v[16:17], v[18:19]
	v_lshlrev_b32_e32 v18, 16, v72
	v_and_b32_e32 v19, 0xffff0000, v72
	v_pk_add_f32 v[18:19], v[10:11], v[18:19]
	v_lshlrev_b32_e32 v10, 16, v73
	v_and_b32_e32 v11, 0xffff0000, v73
	v_pk_add_f32 v[20:21], v[12:13], v[10:11]
	v_cvt_pk_bf16_f32 v10, v14, v15
	v_cvt_pk_bf16_f32 v11, v16, v17
	v_cvt_pk_bf16_f32 v12, v18, v19
	v_cvt_pk_bf16_f32 v13, v20, v21
	s_nor_b64 s[42:43], s[48:49], s[42:43]
	s_and_saveexec_b64 s[46:47], s[42:43]
	s_xor_b64 s[42:43], exec, s[46:47]
	s_cbranch_execz .LBB0_2023
	global_store_dwordx4 v[168:169], v[10:13], off offset:2048

.LBB0_2025:
	s_or_b64 exec, exec, s[42:43]
	v_lshlrev_b32_e32 v12, 16, v66
	v_and_b32_e32 v13, 0xffff0000, v66
	v_pk_add_f32 v[6:7], v[6:7], v[12:13]
	v_lshlrev_b32_e32 v12, 16, v67
	v_and_b32_e32 v13, 0xffff0000, v67
	v_pk_add_f32 v[8:9], v[8:9], v[12:13]
	v_lshlrev_b32_e32 v12, 16, v68
	v_and_b32_e32 v13, 0xffff0000, v68
	v_pk_add_f32 v[12:13], v[2:3], v[12:13]
	v_lshlrev_b32_e32 v2, 16, v69
	v_and_b32_e32 v3, 0xffff0000, v69
	v_pk_add_f32 v[22:23], v[4:5], v[2:3]
	v_cvt_pk_bf16_f32 v2, v6, v7
	v_cvt_pk_bf16_f32 v3, v8, v9
	v_cvt_pk_bf16_f32 v4, v12, v13
	v_cvt_pk_bf16_f32 v5, v22, v23
	s_and_b64 vcc, exec, s[6:7]
	s_mov_b64 s[42:43], -1
	s_cbranch_vccnz .LBB0_2027
	s_mov_b64 s[42:43], 0
	global_store_dwordx4 v[172:173], v[2:5], off offset:2048

.LBB0_2239:
	s_nop 0
	s_nop 0
	s_mov_b32 s98, 0x5000
	s_mov_b32 s99, 0x0
	v_lshl_add_u64 v[240:241], v[166:167], 0, s[98:99]
	s_mov_b32 s98, 0x15000
	s_mov_b32 s99, 0x0
	v_lshl_add_u64 v[242:243], v[166:167], 0, s[98:99]
	global_load_dwordx4 v[122:125], v[240:241], off offset:-4096
	global_load_dwordx4 v[126:129], v[242:243], off offset:-4096
	s_waitcnt vmcnt(8)
	v_lshlrev_b32_e32 v158, 16, v154
	v_and_b32_e32 v159, 0xffff0000, v154
	v_lshlrev_b32_e32 v154, 16, v155
	v_and_b32_e32 v155, 0xffff0000, v155
	v_pk_fma_f32 v[188:189], v[96:97], 0.5, v[154:155] op_sel_hi:[1,0,1]
	v_lshlrev_b32_e32 v154, 16, v156
	v_and_b32_e32 v155, 0xffff0000, v156
	v_pk_fma_f32 v[204:205], v[90:91], 0.5, v[154:155] op_sel_hi:[1,0,1]
	v_lshlrev_b32_e32 v154, 16, v157
	v_and_b32_e32 v155, 0xffff0000, v157
	v_pk_fma_f32 v[158:159], v[94:95], 0.5, v[158:159] op_sel_hi:[1,0,1]
	v_pk_fma_f32 v[206:207], v[92:93], 0.5, v[154:155] op_sel_hi:[1,0,1]
	v_cndmask_b32_e64 v165, 0, 1, s[42:43]
	v_cvt_pk_bf16_f32 v154, v158, v159
	v_cvt_pk_bf16_f32 v155, v188, v189
	v_cvt_pk_bf16_f32 v156, v204, v205
	v_cvt_pk_bf16_f32 v157, v206, v207
	v_cmp_ne_u32_e64 s[12:13], 1, v165
	s_andn2_b64 vcc, exec, s[42:43]
	s_mov_b64 s[14:15], -1
	s_cbranch_vccnz .LBB0_2241
	s_mov_b64 s[14:15], 0
	global_store_dwordx4 v[172:173], v[154:157], off offset:-4096

.LBB0_2249:
	s_or_b64 exec, exec, s[44:45]
	s_waitcnt lgkmcnt(0)
	global_load_dwordx4 v[90:93], v[240:241], off offset:-2048
	global_load_dwordx4 v[94:97], v[242:243], off offset:-2048
	s_waitcnt vmcnt(9)
	v_lshlrev_b32_e32 v154, 16, v150
	v_and_b32_e32 v155, 0xffff0000, v150
	v_lshlrev_b32_e32 v150, 16, v151
	v_and_b32_e32 v151, 0xffff0000, v151
	v_pk_fma_f32 v[156:157], v[120:121], 0.5, v[150:151] op_sel_hi:[1,0,1]
	v_lshlrev_b32_e32 v150, 16, v152
	v_and_b32_e32 v151, 0xffff0000, v152
	v_pk_fma_f32 v[158:159], v[114:115], 0.5, v[150:151] op_sel_hi:[1,0,1]
	v_lshlrev_b32_e32 v150, 16, v153
	v_and_b32_e32 v151, 0xffff0000, v153
	v_pk_fma_f32 v[154:155], v[118:119], 0.5, v[154:155] op_sel_hi:[1,0,1]
	v_pk_fma_f32 v[160:161], v[116:117], 0.5, v[150:151] op_sel_hi:[1,0,1]
	v_cvt_pk_bf16_f32 v150, v154, v155
	v_cvt_pk_bf16_f32 v151, v156, v157
	v_cvt_pk_bf16_f32 v152, v158, v159
	v_cvt_pk_bf16_f32 v153, v160, v161
	s_nor_b64 s[42:43], s[46:47], s[38:39]
	s_and_saveexec_b64 s[44:45], s[42:43]
	s_xor_b64 s[42:43], exec, s[44:45]
	s_cbranch_execz .LBB0_2251
	global_store_dwordx4 v[174:175], v[150:153], off offset:-2048

.LBB0_2253:
	s_or_b64 exec, exec, s[42:43]
	s_nop 0
	global_load_dwordx4 v[114:117], v[240:241], off
	global_load_dwordx4 v[118:121], v[242:243], off
	s_waitcnt vmcnt(10)
	v_lshlrev_b32_e32 v152, 16, v146
	v_and_b32_e32 v153, 0xffff0000, v146
	v_lshlrev_b32_e32 v146, 16, v147
	v_and_b32_e32 v147, 0xffff0000, v147
	v_pk_fma_f32 v[182:183], v[88:89], 0.5, v[146:147] op_sel_hi:[1,0,1]
	v_lshlrev_b32_e32 v146, 16, v148
	v_and_b32_e32 v147, 0xffff0000, v148
	v_pk_fma_f32 v[184:185], v[82:83], 0.5, v[146:147] op_sel_hi:[1,0,1]
	v_lshlrev_b32_e32 v146, 16, v149
	v_and_b32_e32 v147, 0xffff0000, v149
	v_pk_fma_f32 v[152:153], v[86:87], 0.5, v[152:153] op_sel_hi:[1,0,1]
	v_pk_fma_f32 v[186:187], v[84:85], 0.5, v[146:147] op_sel_hi:[1,0,1]
	v_cvt_pk_bf16_f32 v146, v152, v153
	v_cvt_pk_bf16_f32 v147, v182, v183
	v_cvt_pk_bf16_f32 v148, v184, v185
	v_cvt_pk_bf16_f32 v149, v186, v187
	s_and_b64 vcc, exec, s[12:13]
	s_mov_b64 s[42:43], -1
	s_cbranch_vccnz .LBB0_2255
	s_mov_b64 s[42:43], 0
	global_store_dwordx4 v[172:173], v[146:149], off offset:-2048

.LBB0_2263:
	s_or_b64 exec, exec, s[42:43]
	s_waitcnt lgkmcnt(0)
	global_load_dwordx4 v[82:85], v[240:241], off offset:2048
	global_load_dwordx4 v[86:89], v[242:243], off offset:2048
	s_waitcnt vmcnt(11)
	v_lshlrev_b32_e32 v146, 16, v142
	v_and_b32_e32 v147, 0xffff0000, v142
	v_lshlrev_b32_e32 v142, 16, v143
	v_and_b32_e32 v143, 0xffff0000, v143
	v_pk_fma_f32 v[148:149], v[112:113], 0.5, v[142:143] op_sel_hi:[1,0,1]
	v_lshlrev_b32_e32 v142, 16, v144
	v_and_b32_e32 v143, 0xffff0000, v144
	v_pk_fma_f32 v[150:151], v[106:107], 0.5, v[142:143] op_sel_hi:[1,0,1]
	v_lshlrev_b32_e32 v142, 16, v145
	v_and_b32_e32 v143, 0xffff0000, v145
	v_pk_fma_f32 v[146:147], v[110:111], 0.5, v[146:147] op_sel_hi:[1,0,1]
	v_pk_fma_f32 v[152:153], v[108:109], 0.5, v[142:143] op_sel_hi:[1,0,1]
	v_cvt_pk_bf16_f32 v142, v146, v147
	v_cvt_pk_bf16_f32 v143, v148, v149
	v_cvt_pk_bf16_f32 v144, v150, v151
	v_cvt_pk_bf16_f32 v145, v152, v153
	s_nor_b64 s[42:43], s[44:45], s[38:39]
	s_and_saveexec_b64 s[44:45], s[42:43]
	s_xor_b64 s[42:43], exec, s[44:45]
	s_cbranch_execz .LBB0_2265
	global_store_dwordx4 v[174:175], v[142:145], off

.LBB0_2267:
	s_or_b64 exec, exec, s[42:43]
	s_waitcnt vmcnt(10)
	v_lshlrev_b32_e32 v144, 16, v138
	v_and_b32_e32 v145, 0xffff0000, v138
	v_lshlrev_b32_e32 v138, 16, v139
	v_and_b32_e32 v139, 0xffff0000, v139
	v_pk_fma_f32 v[154:155], v[80:81], 0.5, v[138:139] op_sel_hi:[1,0,1]
	v_lshlrev_b32_e32 v138, 16, v140
	v_and_b32_e32 v139, 0xffff0000, v140
	v_pk_fma_f32 v[156:157], v[74:75], 0.5, v[138:139] op_sel_hi:[1,0,1]
	v_lshlrev_b32_e32 v138, 16, v141
	v_and_b32_e32 v139, 0xffff0000, v141
	v_pk_fma_f32 v[144:145], v[78:79], 0.5, v[144:145] op_sel_hi:[1,0,1]
	v_pk_fma_f32 v[158:159], v[76:77], 0.5, v[138:139] op_sel_hi:[1,0,1]
	v_cvt_pk_bf16_f32 v138, v144, v145
	v_cvt_pk_bf16_f32 v139, v154, v155
	v_cvt_pk_bf16_f32 v140, v156, v157
	v_cvt_pk_bf16_f32 v141, v158, v159
	s_and_b64 vcc, exec, s[12:13]
	s_mov_b64 s[42:43], -1
	s_cbranch_vccnz .LBB0_2269
	s_mov_b64 s[42:43], 0
	global_store_dwordx4 v[172:173], v[138:141], off

.LBB0_2277:
	s_or_b64 exec, exec, s[42:43]
	s_waitcnt lgkmcnt(0)
	s_waitcnt vmcnt(9)
	v_lshlrev_b32_e32 v138, 16, v134
	v_and_b32_e32 v139, 0xffff0000, v134
	v_lshlrev_b32_e32 v134, 16, v135
	v_and_b32_e32 v135, 0xffff0000, v135
	v_pk_fma_f32 v[140:141], v[104:105], 0.5, v[134:135] op_sel_hi:[1,0,1]
	v_lshlrev_b32_e32 v134, 16, v136
	v_and_b32_e32 v135, 0xffff0000, v136
	v_pk_fma_f32 v[142:143], v[98:99], 0.5, v[134:135] op_sel_hi:[1,0,1]
	v_lshlrev_b32_e32 v134, 16, v137
	v_and_b32_e32 v135, 0xffff0000, v137
	v_pk_fma_f32 v[138:139], v[102:103], 0.5, v[138:139] op_sel_hi:[1,0,1]
	v_pk_fma_f32 v[144:145], v[100:101], 0.5, v[134:135] op_sel_hi:[1,0,1]
	v_cvt_pk_bf16_f32 v134, v138, v139
	v_cvt_pk_bf16_f32 v135, v140, v141
	v_cvt_pk_bf16_f32 v136, v142, v143
	v_cvt_pk_bf16_f32 v137, v144, v145
	s_nor_b64 s[42:43], s[44:45], s[38:39]
	s_and_saveexec_b64 s[44:45], s[42:43]
	s_xor_b64 s[42:43], exec, s[44:45]
	s_cbranch_execz .LBB0_2279
	global_store_dwordx4 v[174:175], v[134:137], off offset:2048

.LBB0_2281:
	s_or_b64 exec, exec, s[42:43]
	s_waitcnt vmcnt(8)
	v_lshlrev_b32_e32 v136, 16, v130
	v_and_b32_e32 v137, 0xffff0000, v130
	v_lshlrev_b32_e32 v130, 16, v131
	v_and_b32_e32 v131, 0xffff0000, v131
	v_pk_fma_f32 v[146:147], v[72:73], 0.5, v[130:131] op_sel_hi:[1,0,1]
	v_lshlrev_b32_e32 v130, 16, v132
	v_and_b32_e32 v131, 0xffff0000, v132
	v_pk_fma_f32 v[148:149], v[66:67], 0.5, v[130:131] op_sel_hi:[1,0,1]
	v_lshlrev_b32_e32 v130, 16, v133
	v_and_b32_e32 v131, 0xffff0000, v133
	v_pk_fma_f32 v[136:137], v[70:71], 0.5, v[136:137] op_sel_hi:[1,0,1]
	v_pk_fma_f32 v[150:151], v[68:69], 0.5, v[130:131] op_sel_hi:[1,0,1]
	v_cvt_pk_bf16_f32 v130, v136, v137
	v_cvt_pk_bf16_f32 v131, v146, v147
	v_cvt_pk_bf16_f32 v132, v148, v149
	v_cvt_pk_bf16_f32 v133, v150, v151
	s_and_b64 vcc, exec, s[12:13]
	s_mov_b64 s[42:43], -1
	s_cbranch_vccnz .LBB0_2283
	s_mov_b64 s[42:43], 0
	global_store_dwordx4 v[172:173], v[130:133], off offset:2048

.LBB0_2290:
	s_or_b64 exec, exec, s[42:43]
	v_add_u32_e32 v184, 0x80, v162
	s_waitcnt lgkmcnt(0)
	v_lshlrev_b32_e32 v131, 6, v184
	v_lshlrev_b32_e32 v132, 2, v184
	v_lshlrev_b32_e32 v130, 7, v184
	v_and_b32_e32 v131, 0x3c0, v131
	v_and_b32_e32 v132, 32, v132
	v_and_b32_e32 v130, 0x4000, v130
	v_bitop3_b32 v131, v131, v132, v219 bitop3:0x36
	v_or3_b32 v196, v130, v131, v222
	v_add_u32_e32 v176, 0x90, v162
	s_mov_b32 s98, 0x5000
	s_mov_b32 s99, 0x0
	v_lshl_add_u64 v[172:173], v[166:167], 0, s[98:99]
	s_waitcnt vmcnt(4)
	v_mov_b32_e32 v158, v122
	v_mov_b32_e32 v159, v123
	v_mov_b32_e32 v160, v124
	v_mov_b32_e32 v161, v125
	s_mov_b32 s98, 0x15000
	s_mov_b32 s99, 0x0
	v_lshl_add_u64 v[174:175], v[166:167], 0, s[98:99]
	v_mov_b32_e32 v154, v126
	v_mov_b32_e32 v155, v127
	v_mov_b32_e32 v156, v128
	v_mov_b32_e32 v157, v129
	v_add_u32_e32 v168, 0xa0, v162
	v_mov_b32_e32 v150, v90
	v_mov_b32_e32 v151, v91
	v_mov_b32_e32 v152, v92
	v_mov_b32_e32 v153, v93
	v_mov_b32_e32 v146, v94
	v_mov_b32_e32 v147, v95
	v_mov_b32_e32 v148, v96
	v_mov_b32_e32 v149, v97
	v_add_u32_e32 v162, 0xb0, v162
	v_mov_b32_e32 v142, v114
	v_mov_b32_e32 v143, v115
	v_mov_b32_e32 v144, v116
	v_mov_b32_e32 v145, v117
	v_mov_b32_e32 v138, v118
	v_mov_b32_e32 v139, v119
	v_mov_b32_e32 v140, v120
	v_mov_b32_e32 v141, v121
	v_mov_b32_e32 v134, v82
	v_mov_b32_e32 v135, v83
	v_mov_b32_e32 v136, v84
	v_mov_b32_e32 v137, v85
	s_nop 0
	v_mov_b32_e32 v130, v86
	v_mov_b32_e32 v131, v87
	v_mov_b32_e32 v132, v88
	v_mov_b32_e32 v133, v89
	s_and_b64 vcc, exec, s[12:13]
	s_mov_b64 s[42:43], -1
	v_lshlrev_b32_e32 v190, 16, v158
	v_and_b32_e32 v191, 0xffff0000, v158
	v_lshlrev_b32_e32 v158, 16, v159
	v_and_b32_e32 v159, 0xffff0000, v159
	v_pk_fma_f32 v[192:193], v[64:65], 0.5, v[158:159] op_sel_hi:[1,0,1]
	v_lshlrev_b32_e32 v158, 16, v160
	v_and_b32_e32 v159, 0xffff0000, v160
	v_pk_fma_f32 v[200:201], v[58:59], 0.5, v[158:159] op_sel_hi:[1,0,1]
	v_lshlrev_b32_e32 v158, 16, v161
	v_and_b32_e32 v159, 0xffff0000, v161
	v_pk_fma_f32 v[190:191], v[62:63], 0.5, v[190:191] op_sel_hi:[1,0,1]
	v_pk_fma_f32 v[202:203], v[60:61], 0.5, v[158:159] op_sel_hi:[1,0,1]
	v_cvt_pk_bf16_f32 v158, v190, v191
	v_cvt_pk_bf16_f32 v159, v192, v193
	v_cvt_pk_bf16_f32 v160, v200, v201
	v_cvt_pk_bf16_f32 v161, v202, v203
	s_cbranch_vccnz .LBB0_2292
	s_mov_b64 s[42:43], 0
	global_store_dwordx4 v[172:173], v[158:161], off offset:-4096

.LBB0_2294:
	v_lshlrev_b32_e32 v160, 16, v154
	v_and_b32_e32 v161, 0xffff0000, v154
	v_lshlrev_b32_e32 v154, 16, v155
	v_and_b32_e32 v155, 0xffff0000, v155
	v_pk_fma_f32 v[188:189], v[32:33], 0.5, v[154:155] op_sel_hi:[1,0,1]
	v_lshlrev_b32_e32 v154, 16, v156
	v_and_b32_e32 v155, 0xffff0000, v156
	v_pk_fma_f32 v[204:205], v[26:27], 0.5, v[154:155] op_sel_hi:[1,0,1]
	v_lshlrev_b32_e32 v154, 16, v157
	v_and_b32_e32 v155, 0xffff0000, v157
	v_pk_fma_f32 v[160:161], v[30:31], 0.5, v[160:161] op_sel_hi:[1,0,1]
	v_pk_fma_f32 v[206:207], v[28:29], 0.5, v[154:155] op_sel_hi:[1,0,1]
	v_cvt_pk_bf16_f32 v154, v160, v161
	v_cvt_pk_bf16_f32 v155, v188, v189
	v_cvt_pk_bf16_f32 v156, v204, v205
	v_cvt_pk_bf16_f32 v157, v206, v207
	s_and_b64 vcc, exec, s[12:13]
	s_mov_b64 s[42:43], -1
	s_cbranch_vccnz .LBB0_2296
	s_mov_b64 s[42:43], 0
	global_store_dwordx4 v[174:175], v[154:157], off offset:-4096

.LBB0_2304:
	s_or_b64 exec, exec, s[42:43]
	s_waitcnt lgkmcnt(0)
	v_lshlrev_b32_e32 v154, 16, v150
	v_and_b32_e32 v155, 0xffff0000, v150
	v_lshlrev_b32_e32 v150, 16, v151
	v_and_b32_e32 v151, 0xffff0000, v151
	v_pk_fma_f32 v[156:157], v[56:57], 0.5, v[150:151] op_sel_hi:[1,0,1]
	v_lshlrev_b32_e32 v150, 16, v152
	v_and_b32_e32 v151, 0xffff0000, v152
	v_pk_fma_f32 v[158:159], v[50:51], 0.5, v[150:151] op_sel_hi:[1,0,1]
	v_lshlrev_b32_e32 v150, 16, v153
	v_and_b32_e32 v151, 0xffff0000, v153
	v_pk_fma_f32 v[154:155], v[54:55], 0.5, v[154:155] op_sel_hi:[1,0,1]
	v_pk_fma_f32 v[160:161], v[52:53], 0.5, v[150:151] op_sel_hi:[1,0,1]
	v_cvt_pk_bf16_f32 v150, v154, v155
	v_cvt_pk_bf16_f32 v151, v156, v157
	v_cvt_pk_bf16_f32 v152, v158, v159
	v_cvt_pk_bf16_f32 v153, v160, v161
	s_nor_b64 s[42:43], s[44:45], s[38:39]
	s_and_saveexec_b64 s[44:45], s[42:43]
	s_xor_b64 s[42:43], exec, s[44:45]
	s_cbranch_execz .LBB0_2306
	global_store_dwordx4 v[172:173], v[150:153], off offset:-2048

.LBB0_2308:
	s_or_b64 exec, exec, s[42:43]
	s_nop 0
	v_lshlrev_b32_e32 v152, 16, v146
	v_and_b32_e32 v153, 0xffff0000, v146
	v_lshlrev_b32_e32 v146, 16, v147
	v_and_b32_e32 v147, 0xffff0000, v147
	v_pk_fma_f32 v[180:181], v[24:25], 0.5, v[146:147] op_sel_hi:[1,0,1]
	v_lshlrev_b32_e32 v146, 16, v148
	v_and_b32_e32 v147, 0xffff0000, v148
	v_pk_fma_f32 v[182:183], v[18:19], 0.5, v[146:147] op_sel_hi:[1,0,1]
	v_lshlrev_b32_e32 v146, 16, v149
	v_and_b32_e32 v147, 0xffff0000, v149
	v_pk_fma_f32 v[152:153], v[22:23], 0.5, v[152:153] op_sel_hi:[1,0,1]
	v_pk_fma_f32 v[184:185], v[20:21], 0.5, v[146:147] op_sel_hi:[1,0,1]
	v_cvt_pk_bf16_f32 v146, v152, v153
	v_cvt_pk_bf16_f32 v147, v180, v181
	v_cvt_pk_bf16_f32 v148, v182, v183
	v_cvt_pk_bf16_f32 v149, v184, v185
	s_and_b64 vcc, exec, s[12:13]
	s_mov_b64 s[42:43], -1
	s_cbranch_vccnz .LBB0_2310
	s_mov_b64 s[42:43], 0
	global_store_dwordx4 v[174:175], v[146:149], off offset:-2048

.LBB0_2318:
	s_or_b64 exec, exec, s[42:43]
	s_waitcnt lgkmcnt(0)
	v_lshlrev_b32_e32 v146, 16, v142
	v_and_b32_e32 v147, 0xffff0000, v142
	v_lshlrev_b32_e32 v142, 16, v143
	v_and_b32_e32 v143, 0xffff0000, v143
	v_pk_fma_f32 v[148:149], v[48:49], 0.5, v[142:143] op_sel_hi:[1,0,1]
	v_lshlrev_b32_e32 v142, 16, v144
	v_and_b32_e32 v143, 0xffff0000, v144
	v_pk_fma_f32 v[150:151], v[42:43], 0.5, v[142:143] op_sel_hi:[1,0,1]
	v_lshlrev_b32_e32 v142, 16, v145
	v_and_b32_e32 v143, 0xffff0000, v145
	v_pk_fma_f32 v[146:147], v[46:47], 0.5, v[146:147] op_sel_hi:[1,0,1]
	v_pk_fma_f32 v[152:153], v[44:45], 0.5, v[142:143] op_sel_hi:[1,0,1]
	v_cvt_pk_bf16_f32 v142, v146, v147
	v_cvt_pk_bf16_f32 v143, v148, v149
	v_cvt_pk_bf16_f32 v144, v150, v151
	v_cvt_pk_bf16_f32 v145, v152, v153
	s_nor_b64 s[42:43], s[44:45], s[38:39]
	s_and_saveexec_b64 s[44:45], s[42:43]
	s_xor_b64 s[42:43], exec, s[44:45]
	s_cbranch_execz .LBB0_2320
	global_store_dwordx4 v[172:173], v[142:145], off

.LBB0_2322:
	s_or_b64 exec, exec, s[42:43]
	v_lshlrev_b32_e32 v144, 16, v138
	v_and_b32_e32 v145, 0xffff0000, v138
	v_lshlrev_b32_e32 v138, 16, v139
	v_and_b32_e32 v139, 0xffff0000, v139
	v_pk_fma_f32 v[154:155], v[16:17], 0.5, v[138:139] op_sel_hi:[1,0,1]
	v_lshlrev_b32_e32 v138, 16, v140
	v_and_b32_e32 v139, 0xffff0000, v140
	v_pk_fma_f32 v[156:157], v[10:11], 0.5, v[138:139] op_sel_hi:[1,0,1]
	v_lshlrev_b32_e32 v138, 16, v141
	v_and_b32_e32 v139, 0xffff0000, v141
	v_pk_fma_f32 v[144:145], v[14:15], 0.5, v[144:145] op_sel_hi:[1,0,1]
	v_pk_fma_f32 v[158:159], v[12:13], 0.5, v[138:139] op_sel_hi:[1,0,1]
	v_cvt_pk_bf16_f32 v138, v144, v145
	v_cvt_pk_bf16_f32 v139, v154, v155
	v_cvt_pk_bf16_f32 v140, v156, v157
	v_cvt_pk_bf16_f32 v141, v158, v159
	s_and_b64 vcc, exec, s[12:13]
	s_mov_b64 s[42:43], -1
	s_cbranch_vccnz .LBB0_2324
	s_mov_b64 s[42:43], 0
	global_store_dwordx4 v[174:175], v[138:141], off

.LBB0_2332:
	s_or_b64 exec, exec, s[42:43]
	s_waitcnt lgkmcnt(0)
	v_lshlrev_b32_e32 v138, 16, v134
	v_and_b32_e32 v139, 0xffff0000, v134
	v_lshlrev_b32_e32 v134, 16, v135
	v_and_b32_e32 v135, 0xffff0000, v135
	v_pk_fma_f32 v[140:141], v[40:41], 0.5, v[134:135] op_sel_hi:[1,0,1]
	v_lshlrev_b32_e32 v134, 16, v136
	v_and_b32_e32 v135, 0xffff0000, v136
	v_pk_fma_f32 v[142:143], v[34:35], 0.5, v[134:135] op_sel_hi:[1,0,1]
	v_lshlrev_b32_e32 v134, 16, v137
	v_and_b32_e32 v135, 0xffff0000, v137
	v_pk_fma_f32 v[138:139], v[38:39], 0.5, v[138:139] op_sel_hi:[1,0,1]
	v_pk_fma_f32 v[144:145], v[36:37], 0.5, v[134:135] op_sel_hi:[1,0,1]
	v_cvt_pk_bf16_f32 v134, v138, v139
	v_cvt_pk_bf16_f32 v135, v140, v141
	v_cvt_pk_bf16_f32 v136, v142, v143
	v_cvt_pk_bf16_f32 v137, v144, v145
	s_nor_b64 s[38:39], s[44:45], s[38:39]
	s_and_saveexec_b64 s[42:43], s[38:39]
	s_xor_b64 s[38:39], exec, s[42:43]
	s_cbranch_execz .LBB0_2334
	global_store_dwordx4 v[172:173], v[134:137], off offset:2048

.LBB0_2336:
	s_or_b64 exec, exec, s[38:39]
	v_lshlrev_b32_e32 v136, 16, v130
	v_and_b32_e32 v137, 0xffff0000, v130
	v_lshlrev_b32_e32 v130, 16, v131
	v_and_b32_e32 v131, 0xffff0000, v131
	v_pk_fma_f32 v[146:147], v[8:9], 0.5, v[130:131] op_sel_hi:[1,0,1]
	v_lshlrev_b32_e32 v130, 16, v132
	v_and_b32_e32 v131, 0xffff0000, v132
	v_pk_fma_f32 v[148:149], v[2:3], 0.5, v[130:131] op_sel_hi:[1,0,1]
	v_lshlrev_b32_e32 v130, 16, v133
	v_and_b32_e32 v131, 0xffff0000, v133
	v_pk_fma_f32 v[136:137], v[6:7], 0.5, v[136:137] op_sel_hi:[1,0,1]
	v_pk_fma_f32 v[150:151], v[4:5], 0.5, v[130:131] op_sel_hi:[1,0,1]
	v_cvt_pk_bf16_f32 v130, v136, v137
	v_cvt_pk_bf16_f32 v131, v146, v147
	v_cvt_pk_bf16_f32 v132, v148, v149
	v_cvt_pk_bf16_f32 v133, v150, v151
	s_and_b64 vcc, exec, s[12:13]
	s_mov_b64 s[38:39], -1
	s_cbranch_vccnz .LBB0_2338
	s_mov_b64 s[38:39], 0
	global_store_dwordx4 v[174:175], v[130:133], off offset:2048
